# attention staging vmcnt waits re-derived for the loop path (10 younger stores no longer waited on); one vmcnt(0) before the first item
# speedup vs baseline: 1.0189x; 1.0023x over previous
; __device__ __forceinline__ int otid() { int t = threadIdx.x; asm volatile("" : "+v"(t)); return t; }
; __device__ __forceinline__ int obid() { int t = blockIdx.x; asm volatile("" : "+s"(t)); return t; }
; __device__ __forceinline__ void attn_load(const bf16_t* proj, const AttnItem& I, int tid, u32x4 (&kr)[6], u32x4 (&vr)[6], u32x4 (&qr)[2][2]) {
;     const int piece = tid & 7, w = tid >> 6, lane = tid & 63;
; #pragma unroll
;     for (int it = 0; it < 6; ++it) { const int kk = it * 64 + (tid >> 3); const int km = I.nbk0 * 128 - 128 + kk;
;         const size_t tok = I.rowbase + (size_t)(km < 0 ? 0 : km) * I.d + I.r;
;         const u32x4 k4 = *(const u32x4*)(proj + tok * PLD + I.qcol + 1536 + piece * 8), v4 = *(const u32x4*)(proj + tok * PLD + I.qcol + 3072 + piece * 8);
;         kr[it].x = km < 0 ? 0u : k4.x; kr[it].y = km < 0 ? 0u : k4.y; kr[it].z = km < 0 ? 0u : k4.z; kr[it].w = km < 0 ? 0u : k4.w;
;         vr[it].x = km < 0 ? 0u : v4.x; vr[it].y = km < 0 ? 0u : v4.y; vr[it].z = km < 0 ? 0u : v4.z; vr[it].w = km < 0 ? 0u : v4.w; }
; #pragma unroll
;     for (int blk = 0; blk < 2; ++blk) { const int qq = 16 * w + (lane & 15); const size_t tokq = I.rowbase + (size_t)((I.nbk0 + blk) * 128 + qq) * I.d + I.r;
;         qr[blk][0] = *(const u32x4*)(proj + tokq * PLD + I.qcol + 8 * (lane >> 4)); qr[blk][1] = *(const u32x4*)(proj + tokq * PLD + I.qcol + 32 + 8 * (lane >> 4)); }
; __device__ __forceinline__ void phase_mixer(const Params& p, LAS unsigned char* lds, int dry, int which) {
;     const int nb = p.T / SEQ; const int nssd = nb * SSD_HEADS; const int nattn = nb * 3 * 8 * 16; const int G = (int)gridDim.x;
;     int it = obid();
;     for (; it < nssd; it += G) { if (which & 1) { const int x8 = it & 7, y8 = it >> 3; ssd_item(p, lds, y8 >> 2, 4 * x8 + (y8 & 3), dry); } }
;     if ((which & 2) && it < nssd + nattn) {
;         const bf16_t* proj = (const bf16_t*)(p.ws + ws_proj(p.T)); const int tid = otid();
;         float gk[8], gq[2][8];
; #pragma unroll
;         for (int e = 0; e < 8; ++e) { gk[e] = p.k_norm_g[(tid & 7) * 8 + e]; gq[0][e] = p.q_norm_g[8 * ((tid & 63) >> 4) + e]; gq[1][e] = p.q_norm_g[32 + 8 * ((tid & 63) >> 4) + e]; }
;         u32x4 kr[6], vr[6], qr[2][2];
;         AttnItem I = attn_decode(it - nssd);
;         attn_load(proj, I, tid, kr, vr, qr);
.LBB0_329:
	s_mul_i32 s0, s2, 0x1a0
	s_cmp_ge_i32 s4, s0
	v_writelane_b32 v243, s0, 57
	s_cbranch_scc1 .LBB0_337
	v_readlane_b32 s0, v243, 34
	s_sub_i32 s0, s4, s0
	s_ashr_i32 s1, s0, 7
	s_mov_b32 s6, s4
	s_bfe_u32 s4, s0, 0x40003
	s_mul_hi_i32 s0, s1, 0x55555556
	s_lshr_b32 s2, s0, 31
	s_add_i32 s0, s0, s2
	v_mov_b32_e32 v8, v220
	s_mul_i32 s2, s0, -3
	s_add_i32 s7, s2, s1
	v_lshlrev_b32_e32 v0, 3, v8
	v_and_b32_e32 v9, 56, v0
	v_lshrrev_b32_e32 v0, 1, v8
	s_lshl_b32 s2, s7, 1
	v_and_b32_e32 v10, 24, v0
	s_lshr_b32 s1, s4, s2
	v_ashrrev_i32_e32 v0, 2, v8
	v_writelane_b32 v243, s1, 45
	s_lshl_b32 s8, s1, 8
	v_bfi_b32 v0, -16, v0, v8
	s_ashr_i32 s1, s0, 31
	v_add_u32_e32 v0, s8, v0
	s_lshl_b64 s[10:11], s[0:1], 12
	s_bfm_b32 s0, s2, 0
	v_add_u32_e32 v2, 0x80, v0
	s_and_b32 s0, s0, s4
	v_ashrrev_i32_e32 v3, 31, v2
	v_writelane_b32 v243, s0, 49
	v_lshlrev_b64 v[2:3], s2, v[2:3]
	s_or_b32 s0, s10, s0
	v_writelane_b32 v243, s10, 47
	s_mov_b32 s1, s11
	v_lshl_add_u64 v[2:3], v[2:3], 0, s[0:1]
	v_mov_b64_e32 v[4:5], s[14:15]
	v_mad_u64_u32 v[6:7], s[4:5], v2, s33, v[4:5]
	v_writelane_b32 v243, s11, 48
	v_mov_b32_e32 v2, v7
	v_mad_u64_u32 v[2:3], s[4:5], v3, s33, v[2:3]
	v_writelane_b32 v243, s7, 43
	v_writelane_b32 v243, s6, 42
	s_and_b32 s5, s6, 7
	s_lshl_b32 s4, s7, 9
	v_writelane_b32 v243, s5, 51
	s_lshl_b32 s5, s5, 6
	s_or_b32 s4, s4, s5
	s_add_i32 s6, s4, 0x1800
	s_mov_b32 s4, s6
	s_ashr_i32 s7, s6, 31
	v_writelane_b32 v243, s4, 53
	s_waitcnt lgkmcnt(0)
	v_ashrrev_i32_e32 v1, 31, v0
	v_mov_b32_e32 v7, v2
	v_writelane_b32 v243, s5, 54
	s_lshl_b64 s[4:5], s[6:7], 1
	v_lshlrev_b64 v[0:1], s2, v[0:1]
	v_lshl_add_u64 v[2:3], v[6:7], 0, s[4:5]
	v_lshlrev_b32_e32 v168, 1, v10
	v_lshl_add_u64 v[0:1], v[0:1], 0, s[0:1]
	s_waitcnt vmcnt(0)
	v_lshl_add_u64 v[28:29], v[2:3], 0, v[168:169]
	v_mad_u64_u32 v[2:3], s[6:7], v0, s33, v[4:5]
	v_mov_b32_e32 v0, v3
	v_mad_u64_u32 v[0:1], s[6:7], v1, s33, v[0:1]
	v_mov_b32_e32 v3, v0
	v_lshl_add_u64 v[0:1], v[2:3], 0, s[4:5]
	v_lshl_add_u64 v[36:37], v[0:1], 0, v[168:169]
	v_ashrrev_i32_e32 v0, 3, v8
	v_add_u32_e32 v46, s8, v0
	v_max_i32_e32 v0, 0xffffff40, v46
	v_add_u32_e32 v168, 0xc0, v0
	v_lshlrev_b64 v[0:1], s2, v[168:169]
	v_lshl_add_u64 v[0:1], v[0:1], 0, s[0:1]
	v_mad_u64_u32 v[2:3], s[6:7], v0, s33, v[4:5]
	v_mov_b32_e32 v0, v3
	v_mad_u64_u32 v[0:1], s[6:7], v1, s33, v[0:1]
	v_mov_b32_e32 v3, v0
	v_lshl_add_u64 v[0:1], v[2:3], 0, s[4:5]
	v_lshlrev_b32_e32 v168, 1, v9
	v_lshl_add_u64 v[0:1], v[0:1], 0, v[168:169]
	s_movk_i32 s8, 0x1000
	v_add_co_u32_e32 v2, vcc, s8, v0
	v_lshlrev_b32_e32 v20, 2, v10
	s_nop 0
	v_addc_co_u32_e32 v3, vcc, 0, v1, vcc
	global_load_dwordx4 v[40:43], v[2:3], off offset:2048
	global_load_dwordx4 v[56:59], v[0:1], off offset:3072
	v_max_i32_e32 v0, 0xffffff80, v46
	v_add_u32_e32 v0, 0x80, v0
	v_mov_b32_e32 v1, v169
	v_lshlrev_b64 v[0:1], s2, v[0:1]
	v_lshl_add_u64 v[0:1], v[0:1], 0, s[0:1]
	v_mad_u64_u32 v[2:3], s[6:7], v0, s33, v[4:5]
	v_mov_b32_e32 v0, v3
	v_mad_u64_u32 v[0:1], s[6:7], v1, s33, v[0:1]
	v_mov_b32_e32 v3, v0
	v_lshl_add_u64 v[0:1], v[2:3], 0, s[4:5]
	v_lshl_add_u64 v[0:1], v[0:1], 0, v[168:169]
	v_add_co_u32_e32 v2, vcc, s8, v0
	s_nop 1
	v_addc_co_u32_e32 v3, vcc, 0, v1, vcc
	global_load_dwordx4 v[60:63], v[2:3], off offset:2048
	global_load_dwordx4 v[64:67], v[0:1], off offset:3072
	v_max_i32_e32 v0, 0xffffffc0, v46
	v_add_u32_e32 v0, 64, v0
	v_mov_b32_e32 v1, v169
	v_lshlrev_b64 v[0:1], s2, v[0:1]
	v_lshl_add_u64 v[0:1], v[0:1], 0, s[0:1]
	v_mad_u64_u32 v[2:3], s[6:7], v0, s33, v[4:5]
	v_mov_b32_e32 v0, v3
	v_mad_u64_u32 v[0:1], s[6:7], v1, s33, v[0:1]
	v_mov_b32_e32 v3, v0
	v_lshl_add_u64 v[0:1], v[2:3], 0, s[4:5]
	v_lshl_add_u64 v[0:1], v[0:1], 0, v[168:169]
	v_add_co_u32_e32 v2, vcc, s8, v0
	s_nop 1
	v_addc_co_u32_e32 v3, vcc, 0, v1, vcc
	global_load_dwordx4 v[72:75], v[2:3], off offset:2048
	global_load_dwordx4 v[78:81], v[0:1], off offset:3072
	v_max_i32_e32 v0, 0, v46
	v_mov_b32_e32 v1, v169
	v_lshlrev_b64 v[0:1], s2, v[0:1]
	v_lshl_add_u64 v[0:1], v[0:1], 0, s[0:1]
	v_mad_u64_u32 v[2:3], s[6:7], v0, s33, v[4:5]
	v_mov_b32_e32 v0, v3
	v_mad_u64_u32 v[0:1], s[6:7], v1, s33, v[0:1]
	v_mov_b32_e32 v3, v0
	v_lshl_add_u64 v[0:1], v[2:3], 0, s[4:5]
	v_lshl_add_u64 v[0:1], v[0:1], 0, v[168:169]
	v_add_co_u32_e32 v2, vcc, s8, v0
	s_nop 1
	v_addc_co_u32_e32 v3, vcc, 0, v1, vcc
	global_load_dwordx4 v[90:93], v[2:3], off offset:2048
	global_load_dwordx4 v[98:101], v[0:1], off offset:3072
	v_max_i32_e32 v0, 64, v46
	v_subrev_u32_e32 v0, 64, v0
	v_mov_b32_e32 v1, v169
	v_lshlrev_b64 v[0:1], s2, v[0:1]
	v_lshl_add_u64 v[0:1], v[0:1], 0, s[0:1]
	v_mad_u64_u32 v[2:3], s[6:7], v0, s33, v[4:5]
	v_mov_b32_e32 v0, v3
	v_mad_u64_u32 v[0:1], s[6:7], v1, s33, v[0:1]
	v_mov_b32_e32 v3, v0
	v_lshl_add_u64 v[0:1], v[2:3], 0, s[4:5]
	v_lshl_add_u64 v[0:1], v[0:1], 0, v[168:169]
	v_add_co_u32_e32 v2, vcc, s8, v0
	s_nop 1
	v_addc_co_u32_e32 v3, vcc, 0, v1, vcc
	global_load_dwordx4 v[102:105], v[2:3], off offset:2048
	global_load_dwordx4 v[106:109], v[0:1], off offset:3072
	v_max_i32_e32 v0, 0x80, v46
	v_add_u32_e32 v0, 0xffffff80, v0
	v_mov_b32_e32 v1, v169
	v_lshlrev_b64 v[0:1], s2, v[0:1]
	v_lshl_add_u64 v[0:1], v[0:1], 0, s[0:1]
	v_mad_u64_u32 v[2:3], s[0:1], v0, s33, v[4:5]
	v_mov_b32_e32 v0, v3
	v_mad_u64_u32 v[0:1], s[0:1], v1, s33, v[0:1]
	v_mov_b32_e32 v3, v0
	v_lshl_add_u64 v[0:1], v[2:3], 0, s[4:5]
	v_lshl_add_u64 v[0:1], v[0:1], 0, v[168:169]
	v_add_co_u32_e32 v2, vcc, s8, v0
	v_readlane_b32 s4, v245, 47
	s_nop 0
	v_addc_co_u32_e32 v3, vcc, 0, v1, vcc
	v_lshlrev_b32_e32 v4, 2, v9
	v_readlane_b32 s8, v245, 51
	v_readlane_b32 s9, v245, 52
	v_readlane_b32 s10, v245, 53
	v_readlane_b32 s11, v245, 54
	global_load_dwordx4 v[110:113], v[2:3], off offset:2048
	global_load_dwordx4 v[114:117], v[0:1], off offset:3072
	s_nop 2
	global_load_dwordx4 v[0:3], v4, s[10:11]
	s_nop 0
	global_load_dwordx4 v[4:7], v4, s[10:11] offset:16
	s_nop 0
	global_load_dwordx4 v[8:11], v20, s[8:9]
	global_load_dwordx4 v[12:15], v20, s[8:9] offset:16
	global_load_dwordx4 v[16:19], v20, s[8:9] offset:128
	s_nop 0
	global_load_dwordx4 v[20:23], v20, s[8:9] offset:144
	s_nop 0
	global_load_dwordx4 v[24:27], v[28:29], off offset:64
	s_nop 0
	global_load_dwordx4 v[28:31], v[28:29], off
	s_nop 0
	global_load_dwordx4 v[32:35], v[36:37], off offset:64
	s_nop 0
	global_load_dwordx4 v[36:39], v[36:37], off
	s_movk_i32 s0, 0xff40
	v_cmp_gt_i32_e32 vcc, s0, v46
	s_movk_i32 s0, 0xff80
	v_readlane_b32 s17, v245, 60
	s_waitcnt vmcnt(21)
; __device__ __forceinline__ void attn_load(const bf16_t* proj, const AttnItem& I, int tid, u32x4 (&kr)[6], u32x4 (&vr)[6], u32x4 (&qr)[2][2]) {
;     ...
;     for (int it = 0; it < 6; ++it) { const int kk = it * 64 + (tid >> 3); const int km = I.nbk0 * 128 - 128 + kk;
;         const size_t tok = I.rowbase + (size_t)(km < 0 ? 0 : km) * I.d + I.r;
;         const u32x4 k4 = *(const u32x4*)(proj + tok * PLD + I.qcol + 1536 + piece * 8), v4 = *(const u32x4*)(proj + tok * PLD + I.qcol + 3072 + piece * 8);
;         kr[it].x = km < 0 ? 0u : k4.x; kr[it].y = km < 0 ? 0u : k4.y; kr[it].z = km < 0 ? 0u : k4.z; kr[it].w = km < 0 ? 0u : k4.w;
;         vr[it].x = km < 0 ? 0u : v4.x; vr[it].y = km < 0 ? 0u : v4.y; vr[it].z = km < 0 ? 0u : v4.z; vr[it].w = km < 0 ? 0u : v4.w; }
	v_cndmask_b32_e64 v49, v40, 0, vcc
	v_cndmask_b32_e64 v44, v41, 0, vcc
	v_cndmask_b32_e64 v45, v42, 0, vcc
	v_cndmask_b32_e64 v41, v43, 0, vcc
	s_waitcnt vmcnt(20)
	v_cndmask_b32_e64 v55, v56, 0, vcc
	v_cndmask_b32_e64 v54, v57, 0, vcc
	v_cndmask_b32_e64 v53, v58, 0, vcc
	v_cndmask_b32_e64 v52, v59, 0, vcc
	v_cmp_gt_i32_e32 vcc, s0, v46
	s_movk_i32 s0, 0xffc0
	s_lshl_b32 s17, 1, s2
	s_waitcnt vmcnt(19)
	v_cndmask_b32_e64 v56, v60, 0, vcc
	v_cndmask_b32_e64 v57, v61, 0, vcc
	v_cndmask_b32_e64 v50, v62, 0, vcc
	v_cndmask_b32_e64 v51, v63, 0, vcc
	s_waitcnt vmcnt(18)
	v_cndmask_b32_e64 v71, v64, 0, vcc
	v_cndmask_b32_e64 v70, v65, 0, vcc
	v_cndmask_b32_e64 v69, v66, 0, vcc
	v_cndmask_b32_e64 v68, v67, 0, vcc
	v_cmp_gt_i32_e32 vcc, s0, v46
	s_movk_i32 s0, 0x80
	s_mul_i32 s1, s36, 0x880
	s_waitcnt vmcnt(17)
	v_cndmask_b32_e64 v76, v72, 0, vcc
	v_cndmask_b32_e64 v77, v73, 0, vcc
	v_cndmask_b32_e64 v58, v74, 0, vcc
	v_cndmask_b32_e64 v59, v75, 0, vcc
	s_waitcnt vmcnt(16)
	v_cndmask_b32_e64 v89, v78, 0, vcc
	v_cndmask_b32_e64 v88, v79, 0, vcc
	v_cndmask_b32_e64 v85, v80, 0, vcc
	v_cndmask_b32_e64 v84, v81, 0, vcc
	v_cmp_gt_i32_e32 vcc, 0, v46
	v_readlane_b32 s2, v243, 24
	s_add_u32 s1, s2, s1
	s_waitcnt vmcnt(15)
	v_cndmask_b32_e64 v90, v90, 0, vcc
	v_cndmask_b32_e64 v91, v91, 0, vcc
	v_cndmask_b32_e64 v78, v92, 0, vcc
	v_cndmask_b32_e64 v79, v93, 0, vcc
	s_waitcnt vmcnt(14)
	v_cndmask_b32_e64 v97, v98, 0, vcc
	v_cndmask_b32_e64 v96, v99, 0, vcc
	v_cndmask_b32_e64 v95, v100, 0, vcc
	v_cndmask_b32_e64 v94, v101, 0, vcc
	v_cmp_gt_i32_e32 vcc, 64, v46
	v_readlane_b32 s2, v243, 25
	v_readlane_b32 s5, v245, 48
	v_readlane_b32 s6, v245, 49
	v_readlane_b32 s7, v245, 50
	v_readlane_b32 s12, v245, 55
	s_waitcnt vmcnt(13)
	v_cndmask_b32_e64 v98, v102, 0, vcc
	v_cndmask_b32_e64 v99, v103, 0, vcc
	v_cndmask_b32_e64 v92, v104, 0, vcc
	v_cndmask_b32_e64 v93, v105, 0, vcc
	s_waitcnt vmcnt(12)
	v_cndmask_b32_e64 v105, v106, 0, vcc
	v_cndmask_b32_e64 v104, v107, 0, vcc
	v_cndmask_b32_e64 v103, v108, 0, vcc
	v_cndmask_b32_e64 v102, v109, 0, vcc
	v_cmp_gt_i32_e32 vcc, s0, v46
	s_mul_hi_i32 s0, s36, 0x880
	s_addc_u32 s0, s2, s0
	s_add_u32 s1, s1, 0x3104000
	v_writelane_b32 v243, s1, 58
	s_addc_u32 s0, s0, 0
	v_readlane_b32 s13, v245, 56
	v_readlane_b32 s14, v245, 57
	v_readlane_b32 s15, v245, 58
	v_readlane_b32 s16, v245, 59
	v_readlane_b32 s18, v245, 61
	v_readlane_b32 s19, v245, 62
	v_writelane_b32 v243, s0, 59
	s_waitcnt vmcnt(11)
	v_cndmask_b32_e64 v106, v110, 0, vcc
	v_cndmask_b32_e64 v107, v111, 0, vcc
	v_cndmask_b32_e64 v100, v112, 0, vcc
	v_cndmask_b32_e64 v101, v113, 0, vcc
	s_waitcnt vmcnt(10)
	v_cndmask_b32_e64 v111, v114, 0, vcc
	v_cndmask_b32_e64 v110, v115, 0, vcc
	v_cndmask_b32_e64 v109, v116, 0, vcc
	v_cndmask_b32_e64 v108, v117, 0, vcc
	s_waitcnt vmcnt(0)
	s_branch .LBB0_332

; __device__ __forceinline__ unsigned cvt_pk_bf16(float lo, float hi) { unsigned r; asm volatile("v_cvt_pk_bf16_f32 %0, %1, %2" : "=v"(r) : "v"(lo), "v"(hi)); return r; }
; #define LAS __attribute__((address_space(3)))
; __device__ __forceinline__ float bflo(unsigned u) { return __uint_as_float(u << 16); }
; __device__ __forceinline__ float bfhi(unsigned u) { return __uint_as_float(u & 0xffff0000u); }
; __device__ __forceinline__ void attn_item(const Params& p, LAS unsigned char* lds, const AttnItem& I, const AttnItem& N, u32x4 (&kr)[6], u32x4 (&vr)[6], u32x4 (&qr)[2][2],
;                                           const float (&gk)[8], const float (&gq)[2][8], int dry) {
;     ...
;     __syncthreads();
;     { const int piece = tid & 7;
; #pragma unroll
;       for (int it = 0; it < 6; ++it) { const int kk = it * 64 + (tid >> 3);
;           const u32x4 k4 = kr[it], v4 = vr[it];
;           float kf[8]; kf[0] = bflo(k4.x); kf[1] = bfhi(k4.x); kf[2] = bflo(k4.y); kf[3] = bfhi(k4.y); kf[4] = bflo(k4.z); kf[5] = bfhi(k4.z); kf[6] = bflo(k4.w); kf[7] = bfhi(k4.w);
;           float ss = 0.f;
; #pragma unroll
;           for (int e = 0; e < 8; ++e) ss += kf[e] * kf[e];
;           ss += dppf<0xB1>(ss, ss); ss += dppf<0x4E>(ss, ss); ss += dppf<0x141>(ss, ss);
;           const float rs = rsqrtf(ss * (1.0f / 64.0f) + EPS);
;           u32x4 ko; ko.x = cvt_pk_bf16(kf[0] * rs * gk[0], kf[1] * rs * gk[1]); ko.y = cvt_pk_bf16(kf[2] * rs * gk[2], kf[3] * rs * gk[3]);
;           ko.z = cvt_pk_bf16(kf[4] * rs * gk[4], kf[5] * rs * gk[5]); ko.w = cvt_pk_bf16(kf[6] * rs * gk[6], kf[7] * rs * gk[7]);
;           *(LAS u32x4*)(KS + kk * KLD + piece * 8) = ko;
;           LAS bf16_t* vp = VT + (piece * 8) * VLD + kk;
;           vp[0] = (bf16_t)(v4.x & 0xffffu); vp[VLD] = (bf16_t)(v4.x >> 16); vp[2 * VLD] = (bf16_t)(v4.y & 0xffffu); vp[3 * VLD] = (bf16_t)(v4.y >> 16);
;           vp[4 * VLD] = (bf16_t)(v4.z & 0xffffu); vp[5 * VLD] = (bf16_t)(v4.z >> 16); vp[6 * VLD] = (bf16_t)(v4.w & 0xffffu); vp[7 * VLD] = (bf16_t)(v4.w >> 16); } }
.LBB0_332:
	v_mov_b32_e32 v48, v220
	v_lshlrev_b32_e32 v42, 16, v111
	v_and_b32_e32 v43, 0xffff0000, v111
	v_readlane_b32 s6, v243, 42
	v_readlane_b32 s7, v243, 45
	v_readlane_b32 s8, v245, 3
	v_pk_mul_f32 v[60:61], v[42:43], v[42:43]
	v_lshlrev_b32_e32 v40, 3, v48
	v_and_b32_e32 v62, 0xffff0000, v110
	v_lshlrev_b32_e32 v63, 16, v110
	s_lshl_b32 s19, s7, 8
	s_add_i32 s7, s6, s8
	v_readlane_b32 s8, v243, 57
	v_and_b32_e32 v47, 56, v40
	v_pk_mul_f32 v[64:65], v[62:63], v[62:63]
	v_add_f32_e32 v40, v60, v61
	v_readlane_b32 s0, v243, 53
	s_cmp_ge_i32 s7, s8
	v_and_b32_e32 v66, 0xffff0000, v109
	v_lshlrev_b32_e32 v67, 16, v109
	v_add_f32_e32 v40, v65, v40
	v_readlane_b32 s1, v243, 54
	v_readlane_b32 s4, v243, 47
	s_cselect_b64 s[12:13], -1, 0
	v_pk_mul_f32 v[72:73], v[66:67], v[66:67]
	v_add_f32_e32 v40, v64, v40
	v_readlane_b32 s1, v243, 49
	v_readlane_b32 s2, v243, 51
	v_readlane_b32 s10, v243, 43
	v_readlane_b32 s5, v243, 48
	v_writelane_b32 v243, s12, 55
	v_and_b32_e32 v74, 0xffff0000, v108
	v_lshlrev_b32_e32 v75, 16, v108
	v_add_f32_e32 v40, v73, v40
	v_writelane_b32 v243, s13, 56
	v_pk_mul_f32 v[80:81], v[74:75], v[74:75]
	v_add_f32_e32 v40, v72, v40
	s_cmp_lt_i32 s7, s8
	v_writelane_b32 v243, s7, 42
	v_add_f32_e32 v40, v81, v40
	s_cselect_b32 s6, s7, s6
	v_readlane_b32 s7, v243, 34
	v_add_f32_e32 v40, v80, v40
	s_sub_i32 s7, s6, s7
	v_mov_b32_e32 v60, v40
	s_bfe_u32 s8, s7, 0x40003
	s_ashr_i32 s7, s7, 7
	v_mov_b32_dpp v60, v60 quad_perm:[1,0,3,2] row_mask:0xf bank_mask:0xf
	v_readlane_b32 s9, v245, 4
	s_and_b32 s15, s6, 7
	s_mul_hi_i32 s6, s7, 0x55555556
	v_add_f32_e32 v40, v40, v60
	s_lshr_b32 s9, s6, 31
	v_mov_b32_e32 v60, v40
	s_add_i32 s6, s6, s9
	s_mul_i32 s9, s6, -3
	v_mov_b32_dpp v60, v60 quad_perm:[2,3,0,1] row_mask:0xf bank_mask:0xf
	v_add_f32_e32 v40, v40, v60
	s_add_i32 s9, s9, s7
	v_mov_b32_e32 v60, v40
	s_lshl_b32 s18, s9, 1
	s_bfm_b32 s7, s18, 0
	v_mov_b32_dpp v60, v60 row_half_mirror row_mask:0xf bank_mask:0xf
	v_add_f32_e32 v40, v40, v60
	s_and_b32 s14, s7, s8
	s_lshr_b32 s11, s8, s18
	v_fmamk_f32 v40, v40, 0x3c800000, v221
	s_mov_b32 s8, 0x800000
	v_mul_f32_e32 v60, 0x4b800000, v40
	v_cmp_gt_f32_e32 vcc, s8, v40
	s_barrier
	s_nop 0
	v_cndmask_b32_e32 v40, v40, v60, vcc
	v_rsq_f32_e32 v60, v40
	s_ashr_i32 s7, s6, 31
	s_lshl_b64 s[12:13], s[6:7], 12
	v_mul_f32_e32 v61, 0x45800000, v60
	v_cndmask_b32_e32 v65, v60, v61, vcc
	v_mul_f32_e32 v42, v65, v42
	v_mul_f32_e32 v43, v65, v43
	s_waitcnt vmcnt(10)
	v_mul_f32_e32 v42, v0, v42
	v_mul_f32_e32 v43, v1, v43
	v_cvt_pk_bf16_f32 v60, v42, v43
	v_mul_f32_e32 v42, v65, v63
	v_mul_f32_e32 v43, v65, v62
	v_mul_f32_e32 v42, v2, v42
	v_mul_f32_e32 v43, v3, v43
	v_cvt_pk_bf16_f32 v61, v42, v43
	v_mul_f32_e32 v42, v65, v67
	v_mul_f32_e32 v43, v65, v66
	s_waitcnt vmcnt(10)
	v_mul_f32_e32 v42, v4, v42
	v_mul_f32_e32 v43, v5, v43
	s_lshl_b32 s6, s9, 9
	s_lshl_b32 s7, s15, 6
	v_lshlrev_b32_e32 v40, 1, v47
	v_cvt_pk_bf16_f32 v62, v42, v43
	v_mul_f32_e32 v42, v65, v75
	v_mul_f32_e32 v43, v65, v74
	s_or_b32 s6, s6, s7
	v_ashrrev_i32_e32 v46, 3, v48
	v_add_u32_e32 v64, 0, v40
	v_mul_f32_e32 v42, v6, v42
	v_mul_f32_e32 v43, v7, v43
	s_movk_i32 s16, 0x90
	s_add_i32 s22, s6, 0x1800
	v_cvt_pk_bf16_f32 v63, v42, v43
	v_mad_u64_u32 v[42:43], s[6:7], v46, s16, v[64:65]
	v_mul_u32_u24_e32 v47, 0x30e, v47
	ds_write_b128 v42, v[60:63]
	v_lshlrev_b32_e32 v43, 1, v46
	v_lshlrev_b32_e32 v60, 16, v105
	v_and_b32_e32 v61, 0xffff0000, v105
	v_add3_u32 v47, v64, v47, v43
	v_pk_mul_f32 v[62:63], v[60:61], v[60:61]
	v_and_b32_e32 v64, 0xffff0000, v104
	v_lshlrev_b32_e32 v65, 16, v104
	v_pk_mul_f32 v[66:67], v[64:65], v[64:65]
	v_add_f32_e32 v43, v62, v63
	v_and_b32_e32 v72, 0xffff0000, v103
	v_lshlrev_b32_e32 v73, 16, v103
	v_add_f32_e32 v43, v67, v43
	v_pk_mul_f32 v[74:75], v[72:73], v[72:73]
	v_add_f32_e32 v43, v66, v43
	v_and_b32_e32 v80, 0xffff0000, v102
	v_lshlrev_b32_e32 v81, 16, v102
	v_add_f32_e32 v43, v75, v43
	v_pk_mul_f32 v[82:83], v[80:81], v[80:81]
	v_add_f32_e32 v43, v74, v43
	v_add_f32_e32 v43, v83, v43
	v_add_f32_e32 v43, v82, v43
	v_mov_b32_e32 v62, v43
	ds_write_b16 v47, v106 offset:55296
	ds_write_b16_d16_hi v47, v106 offset:56080
	ds_write_b16 v47, v107 offset:56864
	ds_write_b16_d16_hi v47, v107 offset:57648
	ds_write_b16 v47, v100 offset:58432
	v_mov_b32_dpp v62, v62 quad_perm:[1,0,3,2] row_mask:0xf bank_mask:0xf
	v_add_f32_e32 v43, v43, v62
	v_mov_b32_e32 v62, v43
	ds_write_b16_d16_hi v47, v100 offset:59216
	ds_write_b16 v47, v101 offset:60000
	ds_write_b16_d16_hi v47, v101 offset:60784
	v_mov_b32_dpp v62, v62 quad_perm:[2,3,0,1] row_mask:0xf bank_mask:0xf
	v_add_f32_e32 v43, v43, v62
	v_mov_b32_e32 v62, v43
	v_writelane_b32 v243, s9, 43
	v_writelane_b32 v243, s15, 51
	v_mov_b32_dpp v62, v62 row_half_mirror row_mask:0xf bank_mask:0xf
	v_add_f32_e32 v43, v43, v62
	v_fmamk_f32 v43, v43, 0x3c800000, v221
	v_mul_f32_e32 v62, 0x4b800000, v43
	v_cmp_gt_f32_e32 vcc, s8, v43
	v_writelane_b32 v243, s11, 45
	s_lshl_b32 s11, s11, 8
	v_cndmask_b32_e32 v43, v43, v62, vcc
	v_rsq_f32_e32 v43, v43
	v_writelane_b32 v243, s14, 49
	v_add_u32_e32 v143, s11, v46
	s_or_b32 s6, s12, s14
	v_mul_f32_e32 v62, 0x45800000, v43
	v_cndmask_b32_e32 v43, v43, v62, vcc
	v_mul_f32_e32 v60, v43, v60
	v_mul_f32_e32 v61, v43, v61
	v_mul_f32_e32 v60, v0, v60
	v_mul_f32_e32 v61, v1, v61
	v_cvt_pk_bf16_f32 v60, v60, v61
	v_mul_f32_e32 v61, v43, v65
	v_mul_f32_e32 v62, v43, v64
	v_mul_f32_e32 v61, v2, v61
	v_mul_f32_e32 v62, v3, v62
	v_cvt_pk_bf16_f32 v61, v61, v62
	v_mul_f32_e32 v62, v43, v73
	v_mul_f32_e32 v63, v43, v72
	v_mul_f32_e32 v62, v4, v62
	v_mul_f32_e32 v63, v5, v63
	v_cvt_pk_bf16_f32 v62, v62, v63
	v_mul_f32_e32 v63, v43, v81
; __device__ __forceinline__ unsigned cvt_pk_bf16(float lo, float hi) { unsigned r; asm volatile("v_cvt_pk_bf16_f32 %0, %1, %2" : "=v"(r) : "v"(lo), "v"(hi)); return r; }
; #define LAS __attribute__((address_space(3)))
; __device__ __forceinline__ float bflo(unsigned u) { return __uint_as_float(u << 16); }
; __device__ __forceinline__ float bfhi(unsigned u) { return __uint_as_float(u & 0xffff0000u); }
; __device__ __forceinline__ void attn_item(const Params& p, LAS unsigned char* lds, const AttnItem& I, const AttnItem& N, u32x4 (&kr)[6], u32x4 (&vr)[6], u32x4 (&qr)[2][2],
;                                           const float (&gk)[8], const float (&gq)[2][8], int dry) {
;     ...
;       for (int it = 0; it < 6; ++it) { const int kk = it * 64 + (tid >> 3);
;           const u32x4 k4 = kr[it], v4 = vr[it];
;           float kf[8]; kf[0] = bflo(k4.x); kf[1] = bfhi(k4.x); kf[2] = bflo(k4.y); kf[3] = bfhi(k4.y); kf[4] = bflo(k4.z); kf[5] = bfhi(k4.z); kf[6] = bflo(k4.w); kf[7] = bfhi(k4.w);
;           float ss = 0.f;
; #pragma unroll
;           for (int e = 0; e < 8; ++e) ss += kf[e] * kf[e];
;           ss += dppf<0xB1>(ss, ss); ss += dppf<0x4E>(ss, ss); ss += dppf<0x141>(ss, ss);
;           const float rs = rsqrtf(ss * (1.0f / 64.0f) + EPS);
;           u32x4 ko; ko.x = cvt_pk_bf16(kf[0] * rs * gk[0], kf[1] * rs * gk[1]); ko.y = cvt_pk_bf16(kf[2] * rs * gk[2], kf[3] * rs * gk[3]);
;           ko.z = cvt_pk_bf16(kf[4] * rs * gk[4], kf[5] * rs * gk[5]); ko.w = cvt_pk_bf16(kf[6] * rs * gk[6], kf[7] * rs * gk[7]);
;           *(LAS u32x4*)(KS + kk * KLD + piece * 8) = ko;
;           LAS bf16_t* vp = VT + (piece * 8) * VLD + kk;
;           vp[0] = (bf16_t)(v4.x & 0xffffu); vp[VLD] = (bf16_t)(v4.x >> 16); vp[2 * VLD] = (bf16_t)(v4.y & 0xffffu); vp[3 * VLD] = (bf16_t)(v4.y >> 16);
;           vp[4 * VLD] = (bf16_t)(v4.z & 0xffffu); vp[5 * VLD] = (bf16_t)(v4.z >> 16); vp[6 * VLD] = (bf16_t)(v4.w & 0xffffu); vp[7 * VLD] = (bf16_t)(v4.w >> 16); } }
	v_mul_f32_e32 v63, v6, v63
	v_mul_f32_e32 v43, v43, v80
	v_mul_f32_e32 v43, v7, v43
	v_cvt_pk_bf16_f32 v63, v63, v43
	ds_write_b128 v42, v[60:63] offset:9216
	ds_write_b16 v47, v98 offset:55424
	ds_write_b16_d16_hi v47, v98 offset:56208
	ds_write_b16 v47, v99 offset:56992
	ds_write_b16_d16_hi v47, v99 offset:57776
	ds_write_b16 v47, v92 offset:58560
	v_lshlrev_b32_e32 v60, 16, v97
	v_and_b32_e32 v61, 0xffff0000, v97
	v_pk_mul_f32 v[62:63], v[60:61], v[60:61]
	v_and_b32_e32 v64, 0xffff0000, v96
	v_lshlrev_b32_e32 v65, 16, v96
	v_pk_mul_f32 v[66:67], v[64:65], v[64:65]
	v_add_f32_e32 v43, v62, v63
	v_and_b32_e32 v72, 0xffff0000, v95
	v_lshlrev_b32_e32 v73, 16, v95
	v_add_f32_e32 v43, v67, v43
	v_pk_mul_f32 v[74:75], v[72:73], v[72:73]
	v_add_f32_e32 v43, v66, v43
	v_and_b32_e32 v80, 0xffff0000, v94
	v_lshlrev_b32_e32 v81, 16, v94
	v_add_f32_e32 v43, v75, v43
	v_pk_mul_f32 v[82:83], v[80:81], v[80:81]
	v_add_f32_e32 v43, v74, v43
	v_add_f32_e32 v43, v83, v43
	v_add_f32_e32 v43, v82, v43
	v_mov_b32_e32 v62, v43
	ds_write_b16_d16_hi v47, v92 offset:59344
	ds_write_b16 v47, v93 offset:60128
	ds_write_b16_d16_hi v47, v93 offset:60912
	v_mov_b32_dpp v62, v62 quad_perm:[1,0,3,2] row_mask:0xf bank_mask:0xf
	v_add_f32_e32 v43, v43, v62
	v_mov_b32_e32 v62, v43
	v_writelane_b32 v243, s12, 47
	s_mov_b32 s7, s13
	v_mov_b32_dpp v62, v62 quad_perm:[2,3,0,1] row_mask:0xf bank_mask:0xf
	v_add_f32_e32 v43, v43, v62
	v_mov_b32_e32 v62, v43
	v_writelane_b32 v243, s13, 48
	s_ashr_i32 s23, s22, 31
	v_mov_b32_dpp v62, v62 row_half_mirror row_mask:0xf bank_mask:0xf
	v_add_f32_e32 v43, v43, v62
	v_fmamk_f32 v43, v43, 0x3c800000, v221
	v_mul_f32_e32 v62, 0x4b800000, v43
	v_cmp_gt_f32_e32 vcc, s8, v43
	v_readlane_b32 s20, v243, 26
	v_readlane_b32 s21, v243, 27
	v_cndmask_b32_e32 v43, v43, v62, vcc
	v_rsq_f32_e32 v43, v43
	v_add_u32_e32 v150, 64, v143
	v_add_u32_e32 v152, 0x80, v143
	v_add_u32_e32 v155, 0xc0, v143
	v_mul_f32_e32 v62, 0x45800000, v43
	v_cndmask_b32_e32 v43, v43, v62, vcc
	v_mul_f32_e32 v60, v43, v60
	v_mul_f32_e32 v61, v43, v61
	v_mul_f32_e32 v60, v0, v60
	v_mul_f32_e32 v61, v1, v61
	v_cvt_pk_bf16_f32 v60, v60, v61
	v_mul_f32_e32 v61, v43, v65
	v_mul_f32_e32 v62, v43, v64
	v_mul_f32_e32 v61, v2, v61
	v_mul_f32_e32 v62, v3, v62
	v_cvt_pk_bf16_f32 v61, v61, v62
	v_mul_f32_e32 v62, v43, v73
	v_mul_f32_e32 v63, v43, v72
	v_mul_f32_e32 v62, v4, v62
	v_mul_f32_e32 v63, v5, v63
	v_cvt_pk_bf16_f32 v62, v62, v63
	v_mul_f32_e32 v63, v43, v81
	v_mul_f32_e32 v63, v6, v63
	v_mul_f32_e32 v43, v43, v80
	v_mul_f32_e32 v43, v7, v43
	v_cvt_pk_bf16_f32 v63, v63, v43
	ds_write_b128 v42, v[60:63] offset:18432
	ds_write_b16 v47, v90 offset:55552
	ds_write_b16_d16_hi v47, v90 offset:56336
	ds_write_b16 v47, v91 offset:57120
	ds_write_b16_d16_hi v47, v91 offset:57904
	ds_write_b16 v47, v78 offset:58688
	v_lshlrev_b32_e32 v60, 16, v89
	v_and_b32_e32 v61, 0xffff0000, v89
	v_pk_mul_f32 v[62:63], v[60:61], v[60:61]
	v_and_b32_e32 v64, 0xffff0000, v88
	v_lshlrev_b32_e32 v65, 16, v88
	v_pk_mul_f32 v[66:67], v[64:65], v[64:65]
	v_add_f32_e32 v43, v62, v63
	v_and_b32_e32 v72, 0xffff0000, v85
	v_lshlrev_b32_e32 v73, 16, v85
	v_add_f32_e32 v43, v67, v43
	v_pk_mul_f32 v[74:75], v[72:73], v[72:73]
	v_add_f32_e32 v43, v66, v43
	v_and_b32_e32 v80, 0xffff0000, v84
	v_lshlrev_b32_e32 v81, 16, v84
	v_add_f32_e32 v43, v75, v43
	v_pk_mul_f32 v[82:83], v[80:81], v[80:81]
	v_add_f32_e32 v43, v74, v43
	v_add_f32_e32 v43, v83, v43
	v_add_f32_e32 v43, v82, v43
	v_mov_b32_e32 v62, v43
	ds_write_b16_d16_hi v47, v78 offset:59472
	ds_write_b16 v47, v79 offset:60256
	ds_write_b16_d16_hi v47, v79 offset:61040
	v_mov_b32_dpp v62, v62 quad_perm:[1,0,3,2] row_mask:0xf bank_mask:0xf
	v_add_f32_e32 v43, v43, v62
	v_mov_b32_e32 v62, v43
	v_and_b32_e32 v74, 0xffff0000, v68
	v_lshlrev_b32_e32 v75, 16, v68
	v_mov_b32_dpp v62, v62 quad_perm:[2,3,0,1] row_mask:0xf bank_mask:0xf
	v_add_f32_e32 v43, v43, v62
	v_mov_b32_e32 v62, v43
	s_movk_i32 s14, 0x1000
	v_and_b32_e32 v136, 15, v48
	v_mov_b32_dpp v62, v62 row_half_mirror row_mask:0xf bank_mask:0xf
	v_add_f32_e32 v43, v43, v62
	v_fmamk_f32 v43, v43, 0x3c800000, v221
	v_mul_f32_e32 v62, 0x4b800000, v43
	v_cmp_gt_f32_e32 vcc, s8, v43
	v_bfe_u32 v141, v48, 4, 2
	v_lshl_add_u32 v98, v141, 4, 0
	v_cndmask_b32_e32 v43, v43, v62, vcc
	v_rsq_f32_e32 v43, v43
	v_cmp_gt_i32_e64 s[36:37], 0, v152
	v_mul_f32_e32 v62, 0x45800000, v43
	v_cndmask_b32_e32 v43, v43, v62, vcc
	v_mul_f32_e32 v60, v43, v60
	v_mul_f32_e32 v61, v43, v61
	v_mul_f32_e32 v60, v0, v60
	v_mul_f32_e32 v61, v1, v61
	v_cvt_pk_bf16_f32 v60, v60, v61
	v_mul_f32_e32 v61, v43, v65
	v_mul_f32_e32 v62, v43, v64
	v_mul_f32_e32 v61, v2, v61
	v_mul_f32_e32 v62, v3, v62
	v_cvt_pk_bf16_f32 v61, v61, v62
	v_mul_f32_e32 v62, v43, v73
	v_mul_f32_e32 v63, v43, v72
	v_mul_f32_e32 v62, v4, v62
	v_mul_f32_e32 v63, v5, v63
	v_cvt_pk_bf16_f32 v62, v62, v63
	v_mul_f32_e32 v63, v43, v81
	v_mul_f32_e32 v63, v6, v63
	v_mul_f32_e32 v43, v43, v80
	v_mul_f32_e32 v43, v7, v43
	v_cvt_pk_bf16_f32 v63, v63, v43
	ds_write_b128 v42, v[60:63] offset:27648
	ds_write_b16 v47, v76 offset:55680
	ds_write_b16_d16_hi v47, v76 offset:56464
	ds_write_b16 v47, v77 offset:57248
	ds_write_b16_d16_hi v47, v77 offset:58032
	ds_write_b16 v47, v58 offset:58816
	v_lshlrev_b32_e32 v60, 16, v71
	v_and_b32_e32 v61, 0xffff0000, v71
	v_pk_mul_f32 v[62:63], v[60:61], v[60:61]
	v_and_b32_e32 v64, 0xffff0000, v70
	v_lshlrev_b32_e32 v65, 16, v70
	v_pk_mul_f32 v[66:67], v[64:65], v[64:65]
	v_add_f32_e32 v43, v62, v63
	v_and_b32_e32 v70, 0xffff0000, v69
	v_lshlrev_b32_e32 v71, 16, v69
	v_add_f32_e32 v43, v67, v43
	v_pk_mul_f32 v[72:73], v[70:71], v[70:71]
; #define LAS __attribute__((address_space(3)))
; __device__ __forceinline__ void attn_item(const Params& p, LAS unsigned char* lds, const AttnItem& I, const AttnItem& N, u32x4 (&kr)[6], u32x4 (&vr)[6], u32x4 (&qr)[2][2],
;                                           const float (&gk)[8], const float (&gq)[2][8], int dry) {
;     ...
;       for (int it = 0; it < 6; ++it) { const int kk = it * 64 + (tid >> 3);
;           const u32x4 k4 = kr[it], v4 = vr[it];
;           float kf[8]; kf[0] = bflo(k4.x); kf[1] = bfhi(k4.x); kf[2] = bflo(k4.y); kf[3] = bfhi(k4.y); kf[4] = bflo(k4.z); kf[5] = bfhi(k4.z); kf[6] = bflo(k4.w); kf[7] = bfhi(k4.w);
;           float ss = 0.f;
; #pragma unroll
;           for (int e = 0; e < 8; ++e) ss += kf[e] * kf[e];
;           ss += dppf<0xB1>(ss, ss); ss += dppf<0x4E>(ss, ss); ss += dppf<0x141>(ss, ss);
;           const float rs = rsqrtf(ss * (1.0f / 64.0f) + EPS);
;           u32x4 ko; ko.x = cvt_pk_bf16(kf[0] * rs * gk[0], kf[1] * rs * gk[1]); ko.y = cvt_pk_bf16(kf[2] * rs * gk[2], kf[3] * rs * gk[3]);
;           ko.z = cvt_pk_bf16(kf[4] * rs * gk[4], kf[5] * rs * gk[5]); ko.w = cvt_pk_bf16(kf[6] * rs * gk[6], kf[7] * rs * gk[7]);
;           *(LAS u32x4*)(KS + kk * KLD + piece * 8) = ko;
;           LAS bf16_t* vp = VT + (piece * 8) * VLD + kk;
;           vp[0] = (bf16_t)(v4.x & 0xffffu); vp[VLD] = (bf16_t)(v4.x >> 16); vp[2 * VLD] = (bf16_t)(v4.y & 0xffffu); vp[3 * VLD] = (bf16_t)(v4.y >> 16);
;           vp[4 * VLD] = (bf16_t)(v4.z & 0xffffu); vp[5 * VLD] = (bf16_t)(v4.z >> 16); vp[6 * VLD] = (bf16_t)(v4.w & 0xffffu); vp[7 * VLD] = (bf16_t)(v4.w >> 16); } }
;     const int fr = lane & 15, fq = lane >> 4;
;     const int qq = 16 * w + fr;
;     bf16x8 qf[2][2];
; #pragma unroll
;     for (int blk = 0; blk < 2; ++blk) { float qv[2][8]; float ss = 0.f;
; #pragma unroll
;       for (int ks = 0; ks < 2; ++ks) { const u32x4 q4 = qr[blk][ks]; qv[ks][0] = bflo(q4.x); qv[ks][1] = bfhi(q4.x); qv[ks][2] = bflo(q4.y); qv[ks][3] = bfhi(q4.y);
;           qv[ks][4] = bflo(q4.z); qv[ks][5] = bfhi(q4.z); qv[ks][6] = bflo(q4.w); qv[ks][7] = bfhi(q4.w);
; #pragma unroll
;           for (int e = 0; e < 8; ++e) ss += qv[ks][e] * qv[ks][e]; }
;       ss += __shfl_xor(ss, 16); ss += __shfl_xor(ss, 32);
;       const float rs = rsqrtf(ss * (1.0f / 64.0f) + EPS) * 0.125f;
	v_add_f32_e32 v43, v66, v43
	v_add_f32_e32 v43, v73, v43
	v_pk_mul_f32 v[68:69], v[74:75], v[74:75]
	v_add_f32_e32 v43, v72, v43
	v_add_f32_e32 v43, v69, v43
	v_add_f32_e32 v43, v68, v43
	v_mov_b32_e32 v62, v43
	ds_write_b16_d16_hi v47, v58 offset:59600
	ds_write_b16 v47, v59 offset:60384
	ds_write_b16_d16_hi v47, v59 offset:61168
	v_mov_b32_dpp v62, v62 quad_perm:[1,0,3,2] row_mask:0xf bank_mask:0xf
	v_add_f32_e32 v43, v43, v62
	v_mov_b32_e32 v62, v43
	v_lshlrev_b32_e32 v63, 16, v53
	v_and_b32_e32 v66, 0xffff0000, v52
	v_mov_b32_dpp v62, v62 quad_perm:[2,3,0,1] row_mask:0xf bank_mask:0xf
	v_add_f32_e32 v43, v43, v62
	v_mov_b32_e32 v62, v43
	v_lshlrev_b32_e32 v67, 16, v52
	v_ashrrev_i32_e32 v68, 6, v48
	v_mov_b32_dpp v62, v62 row_half_mirror row_mask:0xf bank_mask:0xf
	v_add_f32_e32 v43, v43, v62
	v_fmamk_f32 v43, v43, 0x3c800000, v221
	v_mul_f32_e32 v62, 0x4b800000, v43
	v_cmp_gt_f32_e32 vcc, s8, v43
	v_min_i32_e32 v107, 6, v68
	v_lshlrev_b32_e32 v156, 4, v107
	v_cndmask_b32_e32 v43, v43, v62, vcc
	v_rsq_f32_e32 v43, v43
	v_and_b32_e32 v62, 0xffff0000, v53
	v_pk_mul_f32 v[52:53], v[66:67], v[66:67]
	v_lshl_or_b32 v148, v68, 4, v136
	v_mul_f32_e32 v58, 0x45800000, v43
	v_cndmask_b32_e32 v43, v43, v58, vcc
	v_mul_f32_e32 v58, v43, v60
	v_mul_f32_e32 v59, v43, v61
	v_mul_f32_e32 v58, v0, v58
	v_mul_f32_e32 v59, v1, v59
	v_cvt_pk_bf16_f32 v58, v58, v59
	v_mul_f32_e32 v59, v43, v65
	v_mul_f32_e32 v60, v43, v64
	v_mul_f32_e32 v59, v2, v59
	v_mul_f32_e32 v60, v3, v60
	v_cvt_pk_bf16_f32 v59, v59, v60
	v_mul_f32_e32 v60, v43, v71
	v_mul_f32_e32 v61, v43, v70
	v_mul_f32_e32 v60, v4, v60
	v_mul_f32_e32 v61, v5, v61
	v_cvt_pk_bf16_f32 v60, v60, v61
	v_mul_f32_e32 v61, v43, v75
	v_mul_f32_e32 v61, v6, v61
	v_mul_f32_e32 v43, v43, v74
	v_mul_f32_e32 v43, v7, v43
	v_cvt_pk_bf16_f32 v61, v61, v43
	ds_write_b128 v42, v[58:61] offset:36864
	ds_write_b16 v47, v56 offset:55808
	ds_write_b16_d16_hi v47, v56 offset:56592
	ds_write_b16 v47, v57 offset:57376
	ds_write_b16_d16_hi v47, v57 offset:58160
	ds_write_b16 v47, v50 offset:58944
	v_lshlrev_b32_e32 v56, 16, v55
	v_and_b32_e32 v57, 0xffff0000, v55
	v_pk_mul_f32 v[58:59], v[56:57], v[56:57]
	v_and_b32_e32 v60, 0xffff0000, v54
	v_lshlrev_b32_e32 v61, 16, v54
	v_pk_mul_f32 v[54:55], v[60:61], v[60:61]
	v_add_f32_e32 v43, v58, v59
	v_add_f32_e32 v43, v55, v43
	v_pk_mul_f32 v[64:65], v[62:63], v[62:63]
	v_add_f32_e32 v43, v54, v43
	v_add_f32_e32 v43, v65, v43
	v_add_f32_e32 v43, v64, v43
	v_add_f32_e32 v43, v53, v43
	v_add_f32_e32 v43, v52, v43
	v_mov_b32_e32 v52, v43
	ds_write_b16_d16_hi v47, v50 offset:59728
	ds_write_b16 v47, v51 offset:60512
	ds_write_b16_d16_hi v47, v51 offset:61296
	v_mov_b32_dpp v52, v52 quad_perm:[1,0,3,2] row_mask:0xf bank_mask:0xf
	v_add_f32_e32 v43, v43, v52
	v_mov_b32_e32 v52, v43
	s_waitcnt vmcnt(10)
	v_lshlrev_b32_e32 v54, 16, v37
	v_and_b32_e32 v55, 0xffff0000, v37
	v_mov_b32_dpp v52, v52 quad_perm:[2,3,0,1] row_mask:0xf bank_mask:0xf
	v_add_f32_e32 v43, v43, v52
	v_mov_b32_e32 v52, v43
	v_lshlrev_b32_e32 v58, 16, v39
	v_and_b32_e32 v59, 0xffff0000, v39
	v_mov_b32_dpp v52, v52 row_half_mirror row_mask:0xf bank_mask:0xf
	v_add_f32_e32 v43, v43, v52
	v_fmamk_f32 v43, v43, 0x3c800000, v221
	v_mul_f32_e32 v52, 0x4b800000, v43
	v_cmp_gt_f32_e32 vcc, s8, v43
	v_lshlrev_b32_e32 v37, 16, v32
	v_add_u32_e32 v151, 16, v156
	v_cndmask_b32_e32 v43, v43, v52, vcc
	v_rsq_f32_e32 v43, v43
	v_add_u32_e32 v108, 2, v107
	v_lshlrev_b32_e32 v145, 4, v108
	v_add_u32_e32 v139, 48, v156
	v_mul_f32_e32 v50, 0x45800000, v43
	v_cndmask_b32_e32 v43, v43, v50, vcc
	v_mul_f32_e32 v50, v43, v56
	v_mul_f32_e32 v51, v43, v57
	v_mul_f32_e32 v50, v0, v50
	v_mul_f32_e32 v51, v1, v51
	v_cvt_pk_bf16_f32 v50, v50, v51
	v_mul_f32_e32 v51, v43, v61
	v_mul_f32_e32 v52, v43, v60
	v_mul_f32_e32 v51, v2, v51
	v_mul_f32_e32 v52, v3, v52
	v_cvt_pk_bf16_f32 v51, v51, v52
	v_mul_f32_e32 v52, v43, v63
	v_mul_f32_e32 v53, v43, v62
	v_mul_f32_e32 v52, v4, v52
	v_mul_f32_e32 v53, v5, v53
	v_cvt_pk_bf16_f32 v52, v52, v53
	v_mul_f32_e32 v53, v43, v67
	v_mul_f32_e32 v43, v43, v66
	v_mul_f32_e32 v53, v6, v53
	v_mul_f32_e32 v43, v7, v43
	v_cvt_pk_bf16_f32 v53, v53, v43
	v_and_b32_e32 v43, 64, v224
	ds_write_b128 v42, v[50:53] offset:46080
	ds_write_b16 v47, v49 offset:55936
	ds_write_b16_d16_hi v47, v49 offset:56720
	v_xor_b32_e32 v42, 16, v224
	v_add_u32_e32 v49, 64, v43
	v_cmp_lt_i32_e32 vcc, v42, v49
	v_and_b32_e32 v53, 0xffff0000, v36
	v_lshlrev_b32_e32 v52, 16, v36
	v_cndmask_b32_e32 v42, v224, v42, vcc
	v_lshlrev_b32_e32 v99, 2, v42
	v_mul_f32_e32 v42, v53, v53
	v_fmac_f32_e32 v42, v52, v52
	v_fmac_f32_e32 v42, v54, v54
	v_lshlrev_b32_e32 v56, 16, v38
	v_fmac_f32_e32 v42, v55, v55
	v_and_b32_e32 v57, 0xffff0000, v38
	v_fmac_f32_e32 v42, v56, v56
	v_fmac_f32_e32 v42, v57, v57
	v_fmac_f32_e32 v42, v58, v58
	v_and_b32_e32 v36, 0xffff0000, v32
	v_fmac_f32_e32 v42, v59, v59
	v_pk_mul_f32 v[38:39], v[36:37], v[36:37]
	v_lshlrev_b32_e32 v43, 16, v34
	v_add_f32_e32 v32, v39, v42
	v_add_f32_e32 v42, v38, v32
	v_and_b32_e32 v38, 0xffff0000, v33
	v_lshlrev_b32_e32 v39, 16, v33
	v_pk_mul_f32 v[32:33], v[38:39], v[38:39]
	v_lshlrev_b32_e32 v51, 16, v35
	v_add_f32_e32 v33, v33, v42
	v_and_b32_e32 v42, 0xffff0000, v34
	v_add_f32_e32 v50, v32, v33
	v_pk_mul_f32 v[32:33], v[42:43], v[42:43]
	ds_write_b16 v47, v44 offset:57504
	ds_write_b16_d16_hi v47, v44 offset:58288
	ds_write_b16 v47, v45 offset:59072
	ds_write_b16_d16_hi v47, v45 offset:59856
	v_add_f32_e32 v33, v33, v50
	v_and_b32_e32 v50, 0xffff0000, v35
	v_add_f32_e32 v34, v32, v33
	v_pk_mul_f32 v[32:33], v[50:51], v[50:51]
	ds_write_b16 v47, v41 offset:60640
	ds_write_b16_d16_hi v47, v41 offset:61424
	v_add_f32_e32 v33, v33, v34
	v_add_f32_e32 v32, v32, v33
	ds_bpermute_b32 v33, v99, v32
	v_xor_b32_e32 v34, 32, v224
	v_cmp_lt_i32_e32 vcc, v34, v49
	v_and_b32_e32 v47, 0xffff0000, v28
	v_lshlrev_b32_e32 v45, 16, v28
	v_cndmask_b32_e32 v34, v224, v34, vcc
	v_lshlrev_b32_e32 v106, 2, v34
	s_waitcnt lgkmcnt(0)
; __device__ __forceinline__ unsigned cvt_pk_bf16(float lo, float hi) { unsigned r; asm volatile("v_cvt_pk_bf16_f32 %0, %1, %2" : "=v"(r) : "v"(lo), "v"(hi)); return r; }
; __device__ __forceinline__ float bflo(unsigned u) { return __uint_as_float(u << 16); }
; __device__ __forceinline__ float bfhi(unsigned u) { return __uint_as_float(u & 0xffff0000u); }
; __device__ __forceinline__ void attn_load(const bf16_t* proj, const AttnItem& I, int tid, u32x4 (&kr)[6], u32x4 (&vr)[6], u32x4 (&qr)[2][2]) {
;     ...
;     for (int it = 0; it < 6; ++it) { const int kk = it * 64 + (tid >> 3); const int km = I.nbk0 * 128 - 128 + kk;
;         const size_t tok = I.rowbase + (size_t)(km < 0 ? 0 : km) * I.d + I.r;
;         const u32x4 k4 = *(const u32x4*)(proj + tok * PLD + I.qcol + 1536 + piece * 8), v4 = *(const u32x4*)(proj + tok * PLD + I.qcol + 3072 + piece * 8);
; __device__ __forceinline__ void attn_item(const Params& p, LAS unsigned char* lds, const AttnItem& I, const AttnItem& N, u32x4 (&kr)[6], u32x4 (&vr)[6], u32x4 (&qr)[2][2],
;                                           const float (&gk)[8], const float (&gq)[2][8], int dry) {
;     ...
;     for (int blk = 0; blk < 2; ++blk) { float qv[2][8]; float ss = 0.f;
; #pragma unroll
;       for (int ks = 0; ks < 2; ++ks) { const u32x4 q4 = qr[blk][ks]; qv[ks][0] = bflo(q4.x); qv[ks][1] = bfhi(q4.x); qv[ks][2] = bflo(q4.y); qv[ks][3] = bfhi(q4.y);
;           qv[ks][4] = bflo(q4.z); qv[ks][5] = bfhi(q4.z); qv[ks][6] = bflo(q4.w); qv[ks][7] = bfhi(q4.w);
; #pragma unroll
;           for (int e = 0; e < 8; ++e) ss += qv[ks][e] * qv[ks][e]; }
;       ss += __shfl_xor(ss, 16); ss += __shfl_xor(ss, 32);
;       const float rs = rsqrtf(ss * (1.0f / 64.0f) + EPS) * 0.125f;
; #pragma unroll
;       for (int ks = 0; ks < 2; ++ks) { u32x4 o;
;           o.x = cvt_pk_bf16(qv[ks][0] * rs * gq[ks][0], qv[ks][1] * rs * gq[ks][1]); o.y = cvt_pk_bf16(qv[ks][2] * rs * gq[ks][2], qv[ks][3] * rs * gq[ks][3]);
;           o.z = cvt_pk_bf16(qv[ks][4] * rs * gq[ks][4], qv[ks][5] * rs * gq[ks][5]); o.w = cvt_pk_bf16(qv[ks][6] * rs * gq[ks][6], qv[ks][7] * rs * gq[ks][7]);
;           qf[blk][ks] = __builtin_bit_cast(bf16x8, o); } }
	v_add_f32_e32 v32, v32, v33
	ds_bpermute_b32 v33, v106, v32
	v_lshlrev_b32_e32 v49, 16, v29
	v_and_b32_e32 v28, 0xffff0000, v24
	v_add_u32_e32 v158, 4, v107
	v_lshlrev_b32_e32 v134, 4, v158
	s_waitcnt lgkmcnt(0)
	v_add_f32_e32 v32, v32, v33
	v_fmamk_f32 v32, v32, 0x3c800000, v221
	v_mul_f32_e32 v33, 0x4b800000, v32
	v_cmp_gt_f32_e32 vcc, s8, v32
	v_add_u32_e32 v130, 0x50, v156
	v_add_u32_e32 v159, 6, v107
	v_cndmask_b32_e32 v32, v32, v33, vcc
	v_rsq_f32_e32 v32, v32
	v_lshlrev_b32_e32 v125, 4, v159
	v_add_u32_e32 v121, 0x70, v156
	v_add_u32_e32 v160, 8, v107
	v_mul_f32_e32 v33, 0x45800000, v32
	v_cndmask_b32_e32 v32, v32, v33, vcc
	v_mul_f32_e32 v41, 0x3e000000, v32
	v_mul_f32_e32 v32, v41, v52
	v_mul_f32_e32 v33, v41, v53
	v_mul_f32_e32 v32, v8, v32
	v_mul_f32_e32 v33, v9, v33
	v_cvt_pk_bf16_f32 v32, v32, v33
	v_mul_f32_e32 v33, v41, v54
	v_mul_f32_e32 v34, v41, v55
	v_mul_f32_e32 v33, v10, v33
	v_mul_f32_e32 v34, v11, v34
	v_cvt_pk_bf16_f32 v33, v33, v34
	v_mul_f32_e32 v34, v41, v56
	v_mul_f32_e32 v35, v41, v57
	v_mul_f32_e32 v34, v12, v34
	v_mul_f32_e32 v35, v13, v35
	v_cvt_pk_bf16_f32 v34, v34, v35
	v_mul_f32_e32 v35, v41, v58
	v_mul_f32_e32 v44, v41, v59
	v_mul_f32_e32 v35, v14, v35
	v_mul_f32_e32 v44, v15, v44
	v_mul_f32_e32 v38, v41, v38
	v_cvt_pk_bf16_f32 v35, v35, v44
	v_mul_f32_e32 v44, v19, v38
	v_mul_f32_e32 v38, v47, v47
	v_fmac_f32_e32 v38, v45, v45
	v_and_b32_e32 v52, 0xffff0000, v29
	v_fmac_f32_e32 v38, v49, v49
	v_lshlrev_b32_e32 v53, 16, v30
	v_fmac_f32_e32 v38, v52, v52
	v_and_b32_e32 v54, 0xffff0000, v30
	v_fmac_f32_e32 v38, v53, v53
	v_lshlrev_b32_e32 v55, 16, v31
	v_fmac_f32_e32 v38, v54, v54
	v_and_b32_e32 v56, 0xffff0000, v31
	v_fmac_f32_e32 v38, v55, v55
	v_lshlrev_b32_e32 v29, 16, v24
	v_fmac_f32_e32 v38, v56, v56
	v_pk_mul_f32 v[30:31], v[28:29], v[28:29]
	v_mul_f32_e32 v37, v41, v37
	v_add_f32_e32 v24, v31, v38
	v_add_f32_e32 v38, v30, v24
	v_and_b32_e32 v24, 0xffff0000, v25
	v_lshlrev_b32_e32 v25, 16, v25
	v_pk_mul_f32 v[30:31], v[24:25], v[24:25]
	v_mul_f32_e32 v36, v41, v36
	v_add_f32_e32 v31, v31, v38
	v_mul_f32_e32 v37, v16, v37
	v_mul_f32_e32 v36, v17, v36
	v_add_f32_e32 v57, v30, v31
	v_and_b32_e32 v30, 0xffff0000, v26
	v_lshlrev_b32_e32 v31, 16, v26
	v_cvt_pk_bf16_f32 v36, v37, v36
	v_mul_f32_e32 v37, v41, v39
	v_pk_mul_f32 v[38:39], v[30:31], v[30:31]
	v_mul_f32_e32 v37, v18, v37
	v_add_f32_e32 v26, v39, v57
	v_add_f32_e32 v57, v38, v26
	v_and_b32_e32 v26, 0xffff0000, v27
	v_lshlrev_b32_e32 v27, 16, v27
	v_pk_mul_f32 v[38:39], v[26:27], v[26:27]
	v_cvt_pk_bf16_f32 v37, v37, v44
	v_mul_f32_e32 v43, v41, v43
	v_add_f32_e32 v39, v39, v57
	v_add_f32_e32 v38, v38, v39
	ds_bpermute_b32 v39, v99, v38
	v_mul_f32_e32 v42, v41, v42
	v_mul_f32_e32 v43, v20, v43
	v_lshlrev_b32_e32 v117, 4, v160
	v_add_u32_e32 v114, 0x90, v156
	s_waitcnt lgkmcnt(0)
	v_add_f32_e32 v39, v38, v39
	ds_bpermute_b32 v44, v106, v39
	v_mul_f32_e32 v38, v21, v42
	v_cvt_pk_bf16_f32 v38, v43, v38
	v_mul_f32_e32 v42, v41, v51
	v_mul_f32_e32 v42, v22, v42
	s_waitcnt lgkmcnt(0)
	v_add_f32_e32 v39, v39, v44
	v_fmamk_f32 v39, v39, 0x3c800000, v221
	v_mul_f32_e32 v43, 0x4b800000, v39
	v_cmp_gt_f32_e32 vcc, s8, v39
	s_nop 1
	v_cndmask_b32_e32 v39, v39, v43, vcc
	v_rsq_f32_e32 v43, v39
	v_mul_f32_e32 v39, v41, v50
	v_mul_f32_e32 v39, v23, v39
	v_cvt_pk_bf16_f32 v39, v42, v39
	v_mul_f32_e32 v41, 0x45800000, v43
	v_cndmask_b32_e32 v41, v43, v41, vcc
	v_mul_f32_e32 v41, 0x3e000000, v41
	v_mul_f32_e32 v42, v41, v45
	v_mul_f32_e32 v43, v41, v47
	v_mul_f32_e32 v42, v8, v42
	v_mul_f32_e32 v43, v9, v43
	v_cvt_pk_bf16_f32 v92, v42, v43
	v_mul_f32_e32 v42, v41, v49
	v_mul_f32_e32 v43, v41, v52
	v_mul_f32_e32 v42, v10, v42
	v_mul_f32_e32 v43, v11, v43
	v_cvt_pk_bf16_f32 v93, v42, v43
	v_mul_f32_e32 v42, v41, v53
	v_mul_f32_e32 v43, v41, v54
	v_mul_f32_e32 v42, v12, v42
	v_mul_f32_e32 v43, v13, v43
	v_mul_f32_e32 v24, v41, v24
	v_cvt_pk_bf16_f32 v94, v42, v43
	v_mul_f32_e32 v42, v41, v55
	v_mul_f32_e32 v43, v41, v56
	v_mul_f32_e32 v29, v41, v29
	v_mul_f32_e32 v28, v41, v28
	v_mul_f32_e32 v25, v41, v25
	v_mul_f32_e32 v24, v19, v24
	v_mul_f32_e32 v42, v14, v42
	v_mul_f32_e32 v43, v15, v43
	v_cvt_pk_bf16_f32 v95, v42, v43
	v_mul_f32_e32 v29, v16, v29
	v_mul_f32_e32 v28, v17, v28
	v_cvt_pk_bf16_f32 v88, v29, v28
	v_mul_f32_e32 v25, v18, v25
	v_cvt_pk_bf16_f32 v89, v25, v24
	v_mul_f32_e32 v24, v41, v31
	v_mul_f32_e32 v24, v20, v24
	v_mul_f32_e32 v25, v41, v30
	v_mul_f32_e32 v25, v21, v25
	v_cvt_pk_bf16_f32 v90, v24, v25
	v_mul_f32_e32 v24, v41, v27
	v_mul_f32_e32 v24, v22, v24
	v_mul_f32_e32 v25, v41, v26
	v_mul_f32_e32 v25, v23, v25
	v_cvt_pk_bf16_f32 v91, v24, v25
	v_max_i32_e32 v24, 0x80, v143
	v_add_u32_e32 v168, 0xffffff80, v24
	v_max_i32_e32 v28, 64, v143
	v_lshlrev_b64 v[24:25], s18, v[168:169]
	v_subrev_u32_e32 v168, 64, v28
	v_lshl_add_u64 v[24:25], v[24:25], 0, s[6:7]
	v_mov_b64_e32 v[50:51], s[20:21]
	v_lshlrev_b64 v[28:29], s18, v[168:169]
	v_max_i32_e32 v168, 0, v143
	v_mad_u64_u32 v[26:27], s[8:9], v24, s33, v[50:51]
	v_lshlrev_b64 v[42:43], s18, v[168:169]
	v_mov_b32_e32 v24, v27
	v_lshl_add_u64 v[42:43], v[42:43], 0, s[6:7]
	v_mad_u64_u32 v[24:25], s[8:9], v25, s33, v[24:25]
	v_mad_u64_u32 v[44:45], s[12:13], v42, s33, v[50:51]
	s_mov_b32 s8, s22
	v_mov_b32_e32 v42, v45
	v_writelane_b32 v243, s8, 53
	v_mad_u64_u32 v[42:43], s[12:13], v43, s33, v[42:43]
	s_nop 0
	v_writelane_b32 v243, s9, 54
	s_lshl_b64 s[8:9], s[22:23], 1
	v_mov_b32_e32 v45, v42
	v_max_i32_e32 v168, 0, v150
	v_lshl_add_u64 v[42:43], v[44:45], 0, s[8:9]
	v_lshlrev_b64 v[44:45], s18, v[168:169]
	v_max_i32_e32 v168, 0, v152
	v_lshlrev_b64 v[52:53], s18, v[168:169]
; #define LAS __attribute__((address_space(3)))
; __device__ __forceinline__ void attn_item(const Params& p, LAS unsigned char* lds, const AttnItem& I, const AttnItem& N, u32x4 (&kr)[6], u32x4 (&vr)[6], u32x4 (&qr)[2][2],
;                                           const float (&gk)[8], const float (&gq)[2][8], int dry) {
;     ...
;     __syncthreads();
;     attn_load(proj, N, tid, kr, vr, qr);
;     const int ts = w < 6 ? w : 6;
; #pragma unroll
;     for (int blk = 0; blk < 2; ++blk) {
;         const int nbk = I.nbk0 + blk; const size_t tokq = rowbase + (size_t)(nbk * 128 + qq) * d + r;
;         f32x4 s[10]; float mx = -INFINITY;
; #pragma unroll
;         for (int tt = 0; tt < 10; ++tt) { const int kt = ts + tt; f32x4 a4 = (f32x4){0.f, 0.f, 0.f, 0.f};
; #pragma unroll
;             for (int ks = 0; ks < 2; ++ks) { const bf16x8 a = *(const LAS bf16x8*)(KS + ((blk * 8 + kt) * 16 + fr) * KLD + ks * 32 + 8 * fq); a4 = __builtin_amdgcn_mfma_f32_16x16x32_bf16(a, qf[blk][ks], a4, 0, 0, 0); }
; #pragma unroll
;             for (int i = 0; i < 4; ++i) { const int kk = kt * 16 + 4 * fq + i; const int dist = 128 + qq - kk; const int km = nbk * 128 - 128 + kk;
;                 const bool ok = (dist >= 0) && (dist <= 128) && (km >= 0); a4[i] = ok ? a4[i] : -INFINITY; mx = fmaxf(mx, a4[i]); }
;             s[tt] = a4; }
	v_lshl_add_u64 v[52:53], v[52:53], 0, s[6:7]
	v_mad_u64_u32 v[54:55], s[12:13], v52, s33, v[50:51]
	v_mov_b32_e32 v52, v55
	v_mad_u64_u32 v[52:53], s[12:13], v53, s33, v[52:53]
	v_mov_b32_e32 v55, v52
	v_mov_b32_e32 v41, v169
	v_lshl_add_u64 v[52:53], v[54:55], 0, s[8:9]
	v_max_i32_e32 v168, 0, v155
	v_lshl_add_u64 v[62:63], v[52:53], 0, v[40:41]
	v_lshlrev_b64 v[52:53], s18, v[168:169]
	v_lshl_add_u64 v[28:29], v[28:29], 0, s[6:7]
	v_lshl_add_u64 v[44:45], v[44:45], 0, s[6:7]
	v_lshl_add_u64 v[52:53], v[52:53], 0, s[6:7]
	v_mad_u64_u32 v[30:31], s[12:13], v28, s33, v[50:51]
	v_mad_u64_u32 v[46:47], s[12:13], v44, s33, v[50:51]
	v_mad_u64_u32 v[54:55], s[12:13], v52, s33, v[50:51]
	v_mov_b32_e32 v28, v31
	v_mov_b32_e32 v44, v47
	v_mov_b32_e32 v52, v55
	v_mad_u64_u32 v[28:29], s[12:13], v29, s33, v[28:29]
	v_mad_u64_u32 v[44:45], s[12:13], v45, s33, v[44:45]
	v_mad_u64_u32 v[52:53], s[12:13], v53, s33, v[52:53]
	v_mov_b32_e32 v27, v24
	v_mov_b32_e32 v31, v28
	v_mov_b32_e32 v47, v44
	v_mov_b32_e32 v55, v52
	v_lshl_add_u64 v[24:25], v[26:27], 0, s[8:9]
	v_lshl_add_u64 v[28:29], v[30:31], 0, s[8:9]
	v_lshl_add_u64 v[44:45], v[46:47], 0, s[8:9]
	v_lshl_add_u64 v[52:53], v[54:55], 0, s[8:9]
	v_lshl_add_u64 v[24:25], v[24:25], 0, v[40:41]
	v_lshl_add_u64 v[28:29], v[28:29], 0, v[40:41]
	v_lshl_add_u64 v[42:43], v[42:43], 0, v[40:41]
	v_lshl_add_u64 v[44:45], v[44:45], 0, v[40:41]
	v_lshl_add_u64 v[66:67], v[52:53], 0, v[40:41]
	v_ashrrev_i32_e32 v40, 2, v48
	v_bfi_b32 v40, -16, v40, v48
	v_add_co_u32_e32 v26, vcc, s14, v24
	v_add_u32_e32 v40, s11, v40
	s_nop 0
	v_addc_co_u32_e32 v27, vcc, 0, v25, vcc
	v_ashrrev_i32_e32 v41, 31, v40
	v_add_co_u32_e32 v30, vcc, s14, v28
	v_lshlrev_b64 v[52:53], s18, v[40:41]
	v_add_u32_e32 v40, 0x80, v40
	v_addc_co_u32_e32 v31, vcc, 0, v29, vcc
	v_ashrrev_i32_e32 v41, 31, v40
	v_add_co_u32_e32 v60, vcc, s14, v42
	v_lshlrev_b64 v[40:41], s18, v[40:41]
	s_nop 0
	v_addc_co_u32_e32 v61, vcc, 0, v43, vcc
	v_lshl_add_u64 v[52:53], v[52:53], 0, s[6:7]
	v_lshl_add_u64 v[40:41], v[40:41], 0, s[6:7]
	v_add_co_u32_e32 v46, vcc, s14, v44
	v_mad_u64_u32 v[54:55], s[12:13], v52, s33, v[50:51]
	v_and_b32_e32 v168, 48, v48
	v_mad_u64_u32 v[48:49], s[6:7], v40, s33, v[50:51]
	v_addc_co_u32_e32 v47, vcc, 0, v45, vcc
	v_mov_b32_e32 v52, v55
	v_mov_b32_e32 v40, v49
	v_add_co_u32_e32 v64, vcc, s14, v62
	v_mad_u64_u32 v[52:53], s[12:13], v53, s33, v[52:53]
	v_mad_u64_u32 v[40:41], s[6:7], v41, s33, v[40:41]
	v_addc_co_u32_e32 v65, vcc, 0, v63, vcc
	v_mov_b32_e32 v55, v52
	v_mov_b32_e32 v49, v40
	v_add_co_u32_e32 v100, vcc, s14, v66
	v_lshl_add_u64 v[52:53], v[54:55], 0, s[8:9]
	v_lshl_add_u64 v[40:41], v[48:49], 0, s[8:9]
	s_add_u32 s14, s4, s1
	v_or_b32_e32 v48, v156, v136
	v_lshl_add_u64 v[102:103], v[52:53], 0, v[168:169]
	s_addc_u32 s15, s5, 0
	v_mad_u64_u32 v[52:53], s[4:5], v48, s16, v[98:99]
	s_barrier
	ds_read_b128 v[48:51], v52
	ds_read_b128 v[52:55], v52 offset:64
	s_ashr_i32 s1, s0, 31
	s_lshl_b64 s[0:1], s[0:1], 1
	s_waitcnt lgkmcnt(1)
	v_mfma_f32_16x16x32_bf16 v[48:51], v[48:51], v[32:35], 0
	s_add_u32 s0, s20, s0
	v_lshl_add_u64 v[104:105], v[40:41], 0, v[168:169]
	v_lshlrev_b32_e32 v168, 3, v141
	s_addc_u32 s1, s21, s1
	v_lshlrev_b32_e32 v41, 2, v141
	v_lshl_add_u64 v[96:97], s[0:1], 0, v[168:169]
	s_lshl_b64 s[0:1], s[2:3], 2
	v_readlane_b32 s2, v243, 58
	v_add_u32_e32 v40, 0x80, v148
	s_add_u32 s4, s2, s0
	v_readlane_b32 s0, v243, 59
	s_waitcnt lgkmcnt(0)
	v_mfma_f32_16x16x32_bf16 v[48:51], v[52:55], v[36:39], v[48:51]
	v_or_b32_e32 v153, v156, v41
	v_addc_co_u32_e32 v101, vcc, 0, v67, vcc
	s_addc_u32 s5, s0, s1
	s_sub_i32 s0, 0x7f, s19
	v_sub_u32_e32 v52, v40, v153
	s_movk_i32 s1, 0x81
	v_cmp_gt_u32_e64 s[96:97], s1, v52
	v_cmp_lt_i32_e32 vcc, s0, v153
	s_and_b64 vcc, s[96:97], vcc
	s_movk_i32 s2, 0xff7e
	v_cndmask_b32_e32 v110, v231, v48, vcc
	v_sub_u32_e32 v48, v153, v40
	v_cmp_lt_u32_e64 s[94:95], s2, v48
	v_cmp_le_i32_e32 vcc, s0, v153
	v_writelane_b32 v243, s4, 38
	s_and_b64 vcc, s[94:95], vcc
	v_or_b32_e32 v48, v151, v136
	v_writelane_b32 v243, s5, 39
	v_cndmask_b32_e32 v109, v231, v49, vcc
	v_mad_u64_u32 v[48:49], s[4:5], v48, s16, v[98:99]
	ds_read_b128 v[52:55], v48
	v_or_b32_e32 v154, 2, v153
	v_sub_u32_e32 v56, v40, v154
	v_cmp_gt_u32_e64 s[30:31], s1, v56
	ds_read_b128 v[56:59], v48 offset:64
	v_cmp_lt_i32_e32 vcc, s0, v154
	v_or_b32_e32 v157, 3, v153
	s_waitcnt lgkmcnt(1)
	v_mfma_f32_16x16x32_bf16 v[52:55], v[52:55], v[32:35], 0
	s_and_b64 vcc, s[30:31], vcc
	v_sub_u32_e32 v48, v40, v157
	v_cndmask_b32_e32 v162, v231, v50, vcc
	v_cmp_gt_u32_e64 s[34:35], s1, v48
	v_cmp_lt_i32_e32 vcc, s0, v157
	s_and_b64 vcc, s[34:35], vcc
	v_or_b32_e32 v146, v151, v41
	v_cndmask_b32_e32 v163, v231, v51, vcc
	s_waitcnt lgkmcnt(0)
	v_mfma_f32_16x16x32_bf16 v[48:51], v[56:59], v[36:39], v[52:55]
	v_cmp_lt_i32_e32 vcc, s0, v146
	v_or_b32_e32 v147, 2, v146
	v_sub_u32_e32 v56, v40, v147
	v_sub_u32_e32 v52, v40, v146
	v_cmp_gt_u32_e64 s[86:87], s1, v52
	s_and_b64 vcc, s[86:87], vcc
	s_nop 1
	v_cndmask_b32_e32 v164, v231, v48, vcc
	v_sub_u32_e32 v48, v146, v40
	v_cmp_lt_u32_e64 s[88:89], s2, v48
	v_cmp_le_i32_e32 vcc, s0, v146
	s_and_b64 vcc, s[88:89], vcc
	v_or_b32_e32 v48, v145, v136
	v_cndmask_b32_e32 v165, v231, v49, vcc
	v_mad_u64_u32 v[48:49], s[4:5], v48, s16, v[98:99]
	ds_read_b128 v[52:55], v48
	v_cmp_gt_u32_e64 s[90:91], s1, v56
	ds_read_b128 v[56:59], v48 offset:64
	v_cmp_lt_i32_e32 vcc, s0, v147
	v_or_b32_e32 v149, 3, v146
	s_waitcnt lgkmcnt(1)
; #define LAS __attribute__((address_space(3)))
; __device__ __forceinline__ void attn_item(const Params& p, LAS unsigned char* lds, const AttnItem& I, const AttnItem& N, u32x4 (&kr)[6], u32x4 (&vr)[6], u32x4 (&qr)[2][2],
;                                           const float (&gk)[8], const float (&gq)[2][8], int dry) {
;     ...
;         for (int tt = 0; tt < 10; ++tt) { const int kt = ts + tt; f32x4 a4 = (f32x4){0.f, 0.f, 0.f, 0.f};
; #pragma unroll
;             for (int ks = 0; ks < 2; ++ks) { const bf16x8 a = *(const LAS bf16x8*)(KS + ((blk * 8 + kt) * 16 + fr) * KLD + ks * 32 + 8 * fq); a4 = __builtin_amdgcn_mfma_f32_16x16x32_bf16(a, qf[blk][ks], a4, 0, 0, 0); }
; #pragma unroll
;             for (int i = 0; i < 4; ++i) { const int kk = kt * 16 + 4 * fq + i; const int dist = 128 + qq - kk; const int km = nbk * 128 - 128 + kk;
;                 const bool ok = (dist >= 0) && (dist <= 128) && (km >= 0); a4[i] = ok ? a4[i] : -INFINITY; mx = fmaxf(mx, a4[i]); }
;             s[tt] = a4; }
	v_mfma_f32_16x16x32_bf16 v[52:55], v[52:55], v[32:35], 0
	s_and_b64 vcc, s[90:91], vcc
	v_sub_u32_e32 v48, v40, v149
	v_cndmask_b32_e32 v166, v231, v50, vcc
	v_cmp_gt_u32_e64 s[92:93], s1, v48
	v_cmp_lt_i32_e32 vcc, s0, v149
	s_and_b64 vcc, s[92:93], vcc
	v_or_b32_e32 v140, v145, v41
	v_cndmask_b32_e32 v167, v231, v51, vcc
	s_waitcnt lgkmcnt(0)
	v_mfma_f32_16x16x32_bf16 v[48:51], v[56:59], v[36:39], v[52:55]
	v_cmp_lt_i32_e32 vcc, s0, v140
	v_or_b32_e32 v142, 2, v140
	v_sub_u32_e32 v56, v40, v142
	v_sub_u32_e32 v52, v40, v140
	v_cmp_gt_u32_e64 s[78:79], s1, v52
	s_and_b64 vcc, s[78:79], vcc
	s_nop 1
	v_cndmask_b32_e32 v170, v231, v48, vcc
	v_sub_u32_e32 v48, v140, v40
	v_cmp_lt_u32_e64 s[80:81], s2, v48
	v_cmp_le_i32_e32 vcc, s0, v140
	s_and_b64 vcc, s[80:81], vcc
	v_or_b32_e32 v48, v139, v136
	v_cndmask_b32_e32 v171, v231, v49, vcc
	v_mad_u64_u32 v[48:49], s[4:5], v48, s16, v[98:99]
	ds_read_b128 v[52:55], v48
	v_cmp_gt_u32_e64 s[82:83], s1, v56
	ds_read_b128 v[56:59], v48 offset:64
	v_cmp_lt_i32_e32 vcc, s0, v142
	v_or_b32_e32 v144, 3, v140
	s_waitcnt lgkmcnt(1)
	v_mfma_f32_16x16x32_bf16 v[52:55], v[52:55], v[32:35], 0
	s_and_b64 vcc, s[82:83], vcc
	v_sub_u32_e32 v48, v40, v144
	v_cndmask_b32_e32 v172, v231, v50, vcc
	v_cmp_gt_u32_e64 s[84:85], s1, v48
	v_cmp_lt_i32_e32 vcc, s0, v144
	s_and_b64 vcc, s[84:85], vcc
	v_or_b32_e32 v135, v139, v41
	v_cndmask_b32_e32 v173, v231, v51, vcc
	s_waitcnt lgkmcnt(0)
	v_mfma_f32_16x16x32_bf16 v[48:51], v[56:59], v[36:39], v[52:55]
	v_cmp_lt_i32_e32 vcc, s0, v135
	v_or_b32_e32 v137, 2, v135
	v_sub_u32_e32 v56, v40, v137
	v_sub_u32_e32 v52, v40, v135
	v_cmp_gt_u32_e64 s[70:71], s1, v52
	s_and_b64 vcc, s[70:71], vcc
	s_nop 1
	v_cndmask_b32_e32 v174, v231, v48, vcc
	v_sub_u32_e32 v48, v135, v40
	v_cmp_lt_u32_e64 s[72:73], s2, v48
	v_cmp_le_i32_e32 vcc, s0, v135
	s_and_b64 vcc, s[72:73], vcc
	v_or_b32_e32 v48, v134, v136
	v_cndmask_b32_e32 v175, v231, v49, vcc
	v_mad_u64_u32 v[48:49], s[4:5], v48, s16, v[98:99]
	ds_read_b128 v[52:55], v48
	v_cmp_gt_u32_e64 s[74:75], s1, v56
	ds_read_b128 v[56:59], v48 offset:64
	v_cmp_lt_i32_e32 vcc, s0, v137
	v_or_b32_e32 v138, 3, v135
	s_waitcnt lgkmcnt(1)
	v_mfma_f32_16x16x32_bf16 v[52:55], v[52:55], v[32:35], 0
	s_and_b64 vcc, s[74:75], vcc
	v_sub_u32_e32 v48, v40, v138
	v_cndmask_b32_e32 v176, v231, v50, vcc
	v_cmp_gt_u32_e64 s[76:77], s1, v48
	v_cmp_lt_i32_e32 vcc, s0, v138
	s_and_b64 vcc, s[76:77], vcc
	v_or_b32_e32 v131, v134, v41
	v_cndmask_b32_e32 v177, v231, v51, vcc
	s_waitcnt lgkmcnt(0)
	v_mfma_f32_16x16x32_bf16 v[48:51], v[56:59], v[36:39], v[52:55]
	v_cmp_lt_i32_e32 vcc, s0, v131
	v_or_b32_e32 v132, 2, v131
	v_sub_u32_e32 v56, v40, v132
	v_sub_u32_e32 v52, v40, v131
	v_cmp_gt_u32_e64 s[62:63], s1, v52
	s_and_b64 vcc, s[62:63], vcc
	s_nop 1
	v_cndmask_b32_e32 v178, v231, v48, vcc
	v_sub_u32_e32 v48, v131, v40
	v_cmp_lt_u32_e64 s[64:65], s2, v48
	v_cmp_le_i32_e32 vcc, s0, v131
	s_and_b64 vcc, s[64:65], vcc
	v_or_b32_e32 v48, v130, v136
	v_cndmask_b32_e32 v179, v231, v49, vcc
	v_mad_u64_u32 v[48:49], s[4:5], v48, s16, v[98:99]
	ds_read_b128 v[52:55], v48
	v_cmp_gt_u32_e64 s[66:67], s1, v56
	ds_read_b128 v[56:59], v48 offset:64
	v_cmp_lt_i32_e32 vcc, s0, v132
	v_or_b32_e32 v133, 3, v131
	s_waitcnt lgkmcnt(1)
	v_mfma_f32_16x16x32_bf16 v[52:55], v[52:55], v[32:35], 0
	s_and_b64 vcc, s[66:67], vcc
	v_sub_u32_e32 v48, v40, v133
	v_cndmask_b32_e32 v180, v231, v50, vcc
	v_cmp_gt_u32_e64 s[68:69], s1, v48
	v_cmp_lt_i32_e32 vcc, s0, v133
	s_and_b64 vcc, s[68:69], vcc
	v_or_b32_e32 v127, v130, v41
	v_cndmask_b32_e32 v181, v231, v51, vcc
	s_waitcnt lgkmcnt(0)
	v_mfma_f32_16x16x32_bf16 v[48:51], v[56:59], v[36:39], v[52:55]
	v_cmp_lt_i32_e32 vcc, s0, v127
	v_or_b32_e32 v128, 2, v127
	v_sub_u32_e32 v56, v40, v128
	v_sub_u32_e32 v52, v40, v127
	v_cmp_gt_u32_e64 s[54:55], s1, v52
	s_and_b64 vcc, s[54:55], vcc
	s_nop 1
	v_cndmask_b32_e32 v182, v231, v48, vcc
	v_sub_u32_e32 v48, v127, v40
	v_cmp_lt_u32_e64 s[56:57], s2, v48
	v_cmp_le_i32_e32 vcc, s0, v127
	s_and_b64 vcc, s[56:57], vcc
	v_or_b32_e32 v48, v125, v136
	v_cndmask_b32_e32 v183, v231, v49, vcc
	v_mad_u64_u32 v[48:49], s[4:5], v48, s16, v[98:99]
	ds_read_b128 v[52:55], v48
	v_cmp_gt_u32_e64 s[58:59], s1, v56
	ds_read_b128 v[56:59], v48 offset:64
	v_cmp_lt_i32_e32 vcc, s0, v128
	v_or_b32_e32 v129, 3, v127
	s_waitcnt lgkmcnt(1)
	v_mfma_f32_16x16x32_bf16 v[52:55], v[52:55], v[32:35], 0
	s_and_b64 vcc, s[58:59], vcc
	v_sub_u32_e32 v48, v40, v129
	v_cndmask_b32_e32 v184, v231, v50, vcc
	v_cmp_gt_u32_e64 s[60:61], s1, v48
	v_cmp_lt_i32_e32 vcc, s0, v129
	s_and_b64 vcc, s[60:61], vcc
	v_or_b32_e32 v123, v125, v41
	v_cndmask_b32_e32 v185, v231, v51, vcc
	s_waitcnt lgkmcnt(0)
	v_mfma_f32_16x16x32_bf16 v[48:51], v[56:59], v[36:39], v[52:55]
	v_cmp_lt_i32_e32 vcc, s0, v123
	v_or_b32_e32 v124, 2, v123
	v_or_b32_e32 v126, 3, v123
	v_sub_u32_e32 v52, v40, v123
	v_cmp_gt_u32_e64 s[46:47], s1, v52
	s_and_b64 vcc, s[46:47], vcc
	s_nop 1
	v_cndmask_b32_e32 v186, v231, v48, vcc
	v_sub_u32_e32 v48, v123, v40
	v_cmp_lt_u32_e64 s[48:49], s2, v48
	v_cmp_le_i32_e32 vcc, s0, v123
	v_sub_u32_e32 v48, v40, v124
	s_and_b64 vcc, s[48:49], vcc
	v_cmp_gt_u32_e64 s[12:13], s1, v48
	v_or_b32_e32 v48, v121, v136
	v_cndmask_b32_e32 v187, v231, v49, vcc
	v_mad_u64_u32 v[48:49], s[4:5], v48, s16, v[98:99]
	ds_read_b128 v[52:55], v48
	ds_read_b128 v[56:59], v48 offset:64
	v_cmp_lt_i32_e32 vcc, s0, v124
	s_waitcnt lgkmcnt(1)
	v_mfma_f32_16x16x32_bf16 v[52:55], v[52:55], v[32:35], 0
	s_and_b64 vcc, s[12:13], vcc
	v_sub_u32_e32 v48, v40, v126
	v_cndmask_b32_e32 v188, v231, v50, vcc
	v_cmp_gt_u32_e64 s[52:53], s1, v48
	v_cmp_lt_i32_e32 vcc, s0, v126
	s_and_b64 vcc, s[52:53], vcc
	v_or_b32_e32 v119, v121, v41
	v_cndmask_b32_e32 v189, v231, v51, vcc
	s_waitcnt lgkmcnt(0)
; #define LAS __attribute__((address_space(3)))
; __device__ __forceinline__ void attn_load(const bf16_t* proj, const AttnItem& I, int tid, u32x4 (&kr)[6], u32x4 (&vr)[6], u32x4 (&qr)[2][2]) {
;     ...
;     for (int it = 0; it < 6; ++it) { const int kk = it * 64 + (tid >> 3); const int km = I.nbk0 * 128 - 128 + kk;
;         const size_t tok = I.rowbase + (size_t)(km < 0 ? 0 : km) * I.d + I.r;
;         const u32x4 k4 = *(const u32x4*)(proj + tok * PLD + I.qcol + 1536 + piece * 8), v4 = *(const u32x4*)(proj + tok * PLD + I.qcol + 3072 + piece * 8);
;         kr[it].x = km < 0 ? 0u : k4.x; kr[it].y = km < 0 ? 0u : k4.y; kr[it].z = km < 0 ? 0u : k4.z; kr[it].w = km < 0 ? 0u : k4.w;
;         vr[it].x = km < 0 ? 0u : v4.x; vr[it].y = km < 0 ? 0u : v4.y; vr[it].z = km < 0 ? 0u : v4.z; vr[it].w = km < 0 ? 0u : v4.w; }
; #pragma unroll
;     for (int blk = 0; blk < 2; ++blk) { const int qq = 16 * w + (lane & 15); const size_t tokq = I.rowbase + (size_t)((I.nbk0 + blk) * 128 + qq) * I.d + I.r;
;         qr[blk][0] = *(const u32x4*)(proj + tokq * PLD + I.qcol + 8 * (lane >> 4)); qr[blk][1] = *(const u32x4*)(proj + tokq * PLD + I.qcol + 32 + 8 * (lane >> 4)); }
; __device__ __forceinline__ void attn_item(const Params& p, LAS unsigned char* lds, const AttnItem& I, const AttnItem& N, u32x4 (&kr)[6], u32x4 (&vr)[6], u32x4 (&qr)[2][2],
;                                           const float (&gk)[8], const float (&gq)[2][8], int dry) {
;     ...
;         for (int tt = 0; tt < 10; ++tt) { const int kt = ts + tt; f32x4 a4 = (f32x4){0.f, 0.f, 0.f, 0.f};
; #pragma unroll
;             for (int ks = 0; ks < 2; ++ks) { const bf16x8 a = *(const LAS bf16x8*)(KS + ((blk * 8 + kt) * 16 + fr) * KLD + ks * 32 + 8 * fq); a4 = __builtin_amdgcn_mfma_f32_16x16x32_bf16(a, qf[blk][ks], a4, 0, 0, 0); }
; #pragma unroll
;             for (int i = 0; i < 4; ++i) { const int kk = kt * 16 + 4 * fq + i; const int dist = 128 + qq - kk; const int km = nbk * 128 - 128 + kk;
;                 const bool ok = (dist >= 0) && (dist <= 128) && (km >= 0); a4[i] = ok ? a4[i] : -INFINITY; mx = fmaxf(mx, a4[i]); }
;             s[tt] = a4; }
;         mx = fmaxf(mx, __shfl_xor(mx, 16)); mx = fmaxf(mx, __shfl_xor(mx, 32));
	v_mfma_f32_16x16x32_bf16 v[48:51], v[56:59], v[36:39], v[52:55]
	v_cmp_lt_i32_e32 vcc, s0, v119
	v_or_b32_e32 v120, 2, v119
	v_or_b32_e32 v122, 3, v119
	v_sub_u32_e32 v52, v40, v119
	v_cmp_gt_u32_e64 s[38:39], s1, v52
	s_and_b64 vcc, s[38:39], vcc
	s_nop 1
	v_cndmask_b32_e32 v190, v231, v48, vcc
	v_sub_u32_e32 v48, v119, v40
	v_cmp_lt_u32_e64 s[40:41], s2, v48
	v_cmp_le_i32_e32 vcc, s0, v119
	v_sub_u32_e32 v48, v40, v120
	s_and_b64 vcc, s[40:41], vcc
	v_cmp_gt_u32_e64 s[42:43], s1, v48
	v_or_b32_e32 v48, v117, v136
	v_cndmask_b32_e32 v191, v231, v49, vcc
	v_mad_u64_u32 v[48:49], s[4:5], v48, s16, v[98:99]
	ds_read_b128 v[52:55], v48
	ds_read_b128 v[56:59], v48 offset:64
	v_cmp_lt_i32_e32 vcc, s0, v120
	s_waitcnt lgkmcnt(1)
	v_mfma_f32_16x16x32_bf16 v[52:55], v[52:55], v[32:35], 0
	s_and_b64 vcc, s[42:43], vcc
	v_sub_u32_e32 v48, v40, v122
	v_cndmask_b32_e32 v192, v231, v50, vcc
	v_cmp_gt_u32_e64 s[44:45], s1, v48
	v_cmp_lt_i32_e32 vcc, s0, v122
	s_and_b64 vcc, s[44:45], vcc
	v_or_b32_e32 v115, v117, v41
	v_cndmask_b32_e32 v193, v231, v51, vcc
	s_waitcnt lgkmcnt(0)
	v_mfma_f32_16x16x32_bf16 v[48:51], v[56:59], v[36:39], v[52:55]
	v_cmp_lt_i32_e32 vcc, s0, v115
	v_or_b32_e32 v116, 2, v115
	v_or_b32_e32 v118, 3, v115
	v_sub_u32_e32 v52, v40, v115
	v_cmp_gt_u32_e64 s[22:23], s1, v52
	s_and_b64 vcc, s[22:23], vcc
	s_nop 1
	v_cndmask_b32_e32 v194, v231, v48, vcc
	v_sub_u32_e32 v48, v115, v40
	v_cmp_lt_u32_e64 s[24:25], s2, v48
	v_cmp_le_i32_e32 vcc, s0, v115
	v_sub_u32_e32 v48, v40, v116
	s_and_b64 vcc, s[24:25], vcc
	v_cmp_gt_u32_e64 s[26:27], s1, v48
	v_or_b32_e32 v48, v114, v136
	v_cndmask_b32_e32 v195, v231, v49, vcc
	v_mad_u64_u32 v[48:49], s[4:5], v48, s16, v[98:99]
	ds_read_b128 v[52:55], v48
	ds_read_b128 v[56:59], v48 offset:64
	s_waitcnt lgkmcnt(1)
	v_mfma_f32_16x16x32_bf16 v[32:35], v[52:55], v[32:35], 0
	v_cmp_lt_i32_e32 vcc, s0, v116
	s_and_b64 vcc, s[26:27], vcc
	v_sub_u32_e32 v48, v40, v118
	v_cndmask_b32_e32 v196, v231, v50, vcc
	v_cmp_gt_u32_e64 s[28:29], s1, v48
	v_cmp_lt_i32_e32 vcc, s0, v118
	s_waitcnt lgkmcnt(0)
	v_mfma_f32_16x16x32_bf16 v[32:35], v[56:59], v[36:39], v[32:35]
	v_or_b32_e32 v111, v114, v41
	s_and_b64 vcc, s[28:29], vcc
	v_sub_u32_e32 v36, v40, v111
	v_cndmask_b32_e32 v197, v231, v51, vcc
	v_cmp_gt_u32_e64 s[4:5], s1, v36
	v_cmp_lt_i32_e32 vcc, s0, v111
	v_or_b32_e32 v112, 2, v111
	v_writelane_b32 v243, s4, 60
	s_and_b64 vcc, s[4:5], vcc
	v_cndmask_b32_e32 v198, v231, v32, vcc
	v_sub_u32_e32 v32, v111, v40
	v_writelane_b32 v243, s5, 61
	v_cmp_lt_u32_e64 s[4:5], s2, v32
	v_cmp_le_i32_e32 vcc, s0, v111
	v_sub_u32_e32 v32, v40, v112
	v_writelane_b32 v243, s4, 62
	s_and_b64 vcc, s[4:5], vcc
	v_cndmask_b32_e32 v202, v231, v33, vcc
	v_writelane_b32 v243, s5, 63
	v_cmp_gt_u32_e64 s[4:5], s1, v32
	v_cmp_lt_i32_e32 vcc, s0, v112
	v_or_b32_e32 v113, 3, v111
	v_writelane_b32 v242, s4, 0
	s_and_b64 vcc, s[4:5], vcc
	v_sub_u32_e32 v32, v40, v113
	v_writelane_b32 v242, s5, 1
	v_readlane_b32 s4, v243, 30
	v_cndmask_b32_e32 v203, v231, v34, vcc
	v_cmp_lt_i32_e32 vcc, s0, v113
	v_cmp_gt_u32_e64 s[20:21], s1, v32
	s_mul_hi_i32 s1, s10, s4
	s_mul_i32 s0, s10, s4
	v_writelane_b32 v242, s0, 2
	global_load_dwordx4 v[76:79], v[24:25], off offset:3072
	global_load_dwordx4 v[68:71], v[26:27], off offset:2048
	global_load_dwordx4 v[56:59], v[28:29], off offset:3072
	global_load_dwordx4 v[52:55], v[30:31], off offset:2048
	global_load_dwordx4 v[48:51], v[42:43], off offset:3072
	s_nop 0
	global_load_dwordx4 v[40:43], v[60:61], off offset:2048
	v_writelane_b32 v242, s1, 3
	s_mov_b32 s0, 0xff800000
	v_max3_f32 v24, v110, s0, v109
	v_max3_f32 v24, v24, v162, v163
	v_max3_f32 v24, v24, v164, v165
	v_max3_f32 v24, v24, v166, v167
	v_max3_f32 v24, v24, v170, v171
	v_max3_f32 v24, v24, v172, v173
	v_max3_f32 v24, v24, v174, v175
	v_max3_f32 v24, v24, v176, v177
	v_max3_f32 v24, v24, v178, v179
	v_max3_f32 v24, v24, v180, v181
	v_max3_f32 v24, v24, v182, v183
	v_max3_f32 v24, v24, v184, v185
	v_max3_f32 v24, v24, v186, v187
	v_max3_f32 v24, v24, v188, v189
	v_max3_f32 v24, v24, v190, v191
	v_max3_f32 v24, v24, v192, v193
	v_max3_f32 v24, v24, v194, v195
	s_and_b64 vcc, s[20:21], vcc
	v_max3_f32 v24, v24, v196, v197
	v_cndmask_b32_e32 v204, v231, v35, vcc
	v_max3_f32 v24, v24, v198, v202
	v_max3_f32 v24, v24, v203, v204
	ds_bpermute_b32 v25, v99, v24
	global_load_dwordx4 v[84:87], v[44:45], off offset:3072
	global_load_dwordx4 v[80:83], v[46:47], off offset:2048
	global_load_dwordx4 v[72:75], v[62:63], off offset:3072
	s_nop 0
	global_load_dwordx4 v[60:63], v[64:65], off offset:2048
	s_nop 0
	global_load_dwordx4 v[64:67], v[66:67], off offset:3072
	s_nop 0
	global_load_dwordx4 v[44:47], v[100:101], off offset:2048
	global_load_dwordx4 v[36:39], v[102:103], off
	global_load_dwordx4 v[32:35], v[102:103], off offset:64
	s_movk_i32 s0, 0x310
	v_add_u32_e32 v148, s19, v148
	s_waitcnt lgkmcnt(0)
	v_max_f32_e32 v25, v25, v25
	v_max_f32_e32 v24, v24, v25
	ds_bpermute_b32 v25, v106, v24
	v_readlane_b32 s5, v243, 31
	v_readlane_b32 s6, v243, 32
	v_readlane_b32 s7, v243, 33
	v_cmp_gt_i32_e64 s[8:9], 64, v143
	s_waitcnt lgkmcnt(0)
; __device__ __forceinline__ unsigned cvt_pk_bf16(float lo, float hi) { unsigned r; asm volatile("v_cvt_pk_bf16_f32 %0, %1, %2" : "=v"(r) : "v"(lo), "v"(hi)); return r; }
; #define LAS __attribute__((address_space(3)))
; __device__ __forceinline__ void attn_item(const Params& p, LAS unsigned char* lds, const AttnItem& I, const AttnItem& N, u32x4 (&kr)[6], u32x4 (&vr)[6], u32x4 (&qr)[2][2],
;                                           const float (&gk)[8], const float (&gq)[2][8], int dry) {
;     ...
;         mx = fmaxf(mx, __shfl_xor(mx, 16)); mx = fmaxf(mx, __shfl_xor(mx, 32));
;         float den = 0.f;
; #pragma unroll
;         for (int tt = 0; tt < 10; ++tt)
; #pragma unroll
;             for (int i = 0; i < 4; ++i) { const float e = __expf(s[tt][i] - mx); s[tt][i] = e; den += e; }
;         den += __shfl_xor(den, 16); den += __shfl_xor(den, 32);
;         f32x4 ao[4];
; #pragma unroll
;         for (int mt = 0; mt < 4; ++mt) ao[mt] = (f32x4){0.f, 0.f, 0.f, 0.f};
; #pragma unroll
;         for (int kp = 0; kp < 5; ++kp) {
;             u32x4 pk; pk.x = cvt_pk_bf16(s[2 * kp][0], s[2 * kp][1]); pk.y = cvt_pk_bf16(s[2 * kp][2], s[2 * kp][3]); pk.z = cvt_pk_bf16(s[2 * kp + 1][0], s[2 * kp + 1][1]); pk.w = cvt_pk_bf16(s[2 * kp + 1][2], s[2 * kp + 1][3]);
;             const bf16x8 pb = __builtin_bit_cast(bf16x8, pk);
; #pragma unroll
;             for (int mt = 0; mt < 4; ++mt) { const LAS bf16_t* vp = VT + (mt * 16 + fr) * VLD + blk * 128 + (ts + 2 * kp) * 16 + 4 * fq;
;                 const u32x2 lo = *(const LAS u32x2*)vp; const u32x2 hi = *(const LAS u32x2*)(vp + 16);
;                 u32x4 av; av.x = lo.x; av.y = lo.y; av.z = hi.x; av.w = hi.y;
;                 ao[mt] = __builtin_amdgcn_mfma_f32_16x16x32_bf16(__builtin_bit_cast(bf16x8, av), pb, ao[mt], 0, 0, 0); } }
	v_max_f32_e32 v25, v25, v25
	v_max_f32_e32 v161, v24, v25
	v_sub_f32_e32 v103, v162, v161
	v_sub_f32_e32 v162, v166, v161
	v_mul_f32_e32 v162, 0x3fb8aa3b, v162
	v_sub_f32_e32 v24, v110, v161
	v_sub_f32_e32 v110, v165, v161
	v_exp_f32_e32 v165, v162
	v_sub_f32_e32 v162, v167, v161
	v_mul_f32_e32 v162, 0x3fb8aa3b, v162
	v_exp_f32_e32 v166, v162
	v_sub_f32_e32 v162, v170, v161
	v_mul_f32_e32 v162, 0x3fb8aa3b, v162
	v_exp_f32_e32 v167, v162
	v_sub_f32_e32 v162, v171, v161
	v_mul_f32_e32 v24, 0x3fb8aa3b, v24
	v_mul_f32_e32 v162, 0x3fb8aa3b, v162
	v_exp_f32_e32 v100, v24
	global_load_dwordx4 v[28:31], v[104:105], off
	global_load_dwordx4 v[24:27], v[104:105], off offset:64
	v_sub_u32_e32 v105, v98, v168
	v_exp_f32_e32 v168, v162
	v_sub_f32_e32 v162, v172, v161
	v_mul_f32_e32 v162, 0x3fb8aa3b, v162
	v_exp_f32_e32 v199, v162
	v_sub_f32_e32 v162, v173, v161
	v_mul_f32_e32 v162, 0x3fb8aa3b, v162
	v_exp_f32_e32 v200, v162
	v_sub_f32_e32 v162, v174, v161
	v_mul_f32_e32 v162, 0x3fb8aa3b, v162
	v_exp_f32_e32 v201, v162
	v_sub_f32_e32 v162, v175, v161
	v_mul_f32_e32 v162, 0x3fb8aa3b, v162
	v_exp_f32_e32 v205, v162
	v_sub_f32_e32 v162, v176, v161
	v_mul_f32_e32 v162, 0x3fb8aa3b, v162
	v_exp_f32_e32 v206, v162
	v_sub_f32_e32 v162, v177, v161
	v_mul_f32_e32 v162, 0x3fb8aa3b, v162
	v_exp_f32_e32 v207, v162
	v_sub_f32_e32 v162, v178, v161
	v_sub_f32_e32 v102, v109, v161
	v_mul_f32_e32 v162, 0x3fb8aa3b, v162
	v_mul_f32_e32 v102, 0x3fb8aa3b, v102
	v_exp_f32_e32 v208, v162
	v_sub_f32_e32 v162, v179, v161
	v_exp_f32_e32 v102, v102
	v_mul_f32_e32 v103, 0x3fb8aa3b, v103
	v_sub_f32_e32 v104, v163, v161
	v_mul_f32_e32 v162, 0x3fb8aa3b, v162
	v_exp_f32_e32 v103, v103
	v_mul_f32_e32 v104, 0x3fb8aa3b, v104
	v_sub_f32_e32 v109, v164, v161
	v_exp_f32_e32 v209, v162
	v_sub_f32_e32 v162, v180, v161
	v_exp_f32_e32 v104, v104
	v_mul_f32_e32 v109, 0x3fb8aa3b, v109
	v_mul_f32_e32 v162, 0x3fb8aa3b, v162
	v_add_f32_e32 v101, 0, v100
	v_exp_f32_e32 v109, v109
	v_mul_f32_e32 v110, 0x3fb8aa3b, v110
	v_exp_f32_e32 v210, v162
	v_sub_f32_e32 v162, v181, v161
	v_add_f32_e32 v101, v102, v101
	v_exp_f32_e32 v110, v110
	v_mul_f32_e32 v162, 0x3fb8aa3b, v162
	v_add_f32_e32 v101, v103, v101
	v_exp_f32_e32 v211, v162
	v_sub_f32_e32 v162, v182, v161
	v_add_f32_e32 v101, v104, v101
	v_mul_f32_e32 v162, 0x3fb8aa3b, v162
	v_add_f32_e32 v101, v109, v101
	v_exp_f32_e32 v212, v162
	v_sub_f32_e32 v162, v183, v161
	v_add_f32_e32 v101, v110, v101
	v_mul_f32_e32 v162, 0x3fb8aa3b, v162
	v_add_f32_e32 v101, v165, v101
	v_exp_f32_e32 v213, v162
	v_sub_f32_e32 v162, v184, v161
	v_add_f32_e32 v101, v166, v101
	v_mul_f32_e32 v162, 0x3fb8aa3b, v162
	v_add_f32_e32 v101, v167, v101
	v_exp_f32_e32 v214, v162
	v_sub_f32_e32 v162, v185, v161
	v_add_f32_e32 v101, v168, v101
	v_mul_f32_e32 v162, 0x3fb8aa3b, v162
	v_add_f32_e32 v101, v199, v101
	v_exp_f32_e32 v215, v162
	v_sub_f32_e32 v162, v186, v161
	v_add_f32_e32 v101, v200, v101
	v_mul_f32_e32 v162, 0x3fb8aa3b, v162
	v_add_f32_e32 v101, v201, v101
	v_exp_f32_e32 v216, v162
	v_sub_f32_e32 v162, v187, v161
	v_add_f32_e32 v101, v205, v101
	v_mul_f32_e32 v162, 0x3fb8aa3b, v162
	v_add_f32_e32 v101, v206, v101
	v_exp_f32_e32 v217, v162
	v_sub_f32_e32 v162, v188, v161
	v_add_f32_e32 v101, v207, v101
	v_mul_f32_e32 v162, 0x3fb8aa3b, v162
	v_add_f32_e32 v101, v208, v101
	v_exp_f32_e32 v218, v162
	v_sub_f32_e32 v162, v189, v161
	v_add_f32_e32 v101, v209, v101
	v_mul_f32_e32 v162, 0x3fb8aa3b, v162
	v_add_f32_e32 v101, v210, v101
	v_exp_f32_e32 v219, v162
	v_sub_f32_e32 v162, v190, v161
	v_add_f32_e32 v101, v211, v101
	v_mul_f32_e32 v162, 0x3fb8aa3b, v162
	v_add_f32_e32 v101, v212, v101
	v_exp_f32_e32 v235, v162
	v_sub_f32_e32 v162, v191, v161
	v_add_f32_e32 v101, v213, v101
	v_mul_f32_e32 v162, 0x3fb8aa3b, v162
	v_add_f32_e32 v101, v214, v101
	v_exp_f32_e32 v236, v162
	v_sub_f32_e32 v162, v192, v161
	v_add_f32_e32 v101, v215, v101
	v_mul_f32_e32 v162, 0x3fb8aa3b, v162
	v_add_f32_e32 v101, v216, v101
	v_exp_f32_e32 v237, v162
	v_sub_f32_e32 v162, v193, v161
	v_add_f32_e32 v101, v217, v101
	v_mul_f32_e32 v162, 0x3fb8aa3b, v162
	v_add_f32_e32 v101, v218, v101
	v_exp_f32_e32 v238, v162
	v_sub_f32_e32 v162, v194, v161
	v_add_f32_e32 v101, v219, v101
	v_mul_f32_e32 v162, 0x3fb8aa3b, v162
	v_add_f32_e32 v101, v235, v101
	v_exp_f32_e32 v239, v162
	v_add_f32_e32 v101, v236, v101
	v_add_f32_e32 v101, v237, v101
	v_cvt_pk_bf16_f32 v162, v100, v102
	v_cvt_pk_bf16_f32 v163, v103, v104
	v_cvt_pk_bf16_f32 v164, v109, v110
	v_lshl_add_u32 v110, v107, 5, v105
	v_add_f32_e32 v101, v238, v101
	v_mad_u32_u24 v100, v136, s0, v110
	v_add_f32_e32 v240, v239, v101
	v_sub_f32_e32 v101, v195, v161
	v_add_u32_e32 v100, 0xd800, v100
	v_mul_f32_e32 v174, 0x3fb8aa3b, v101
	v_cvt_pk_bf16_f32 v165, v165, v166
	ds_read2_b64 v[100:103], v100 offset1:4
	v_add_u32_e32 v107, 0xd800, v110
	v_mad_u32_u24 v104, v136, s0, v232
	v_add_u32_e32 v109, v107, v104
	ds_read2_b64 v[170:173], v109 offset1:4
	v_exp_f32_e32 v166, v174
	v_sub_f32_e32 v109, v196, v161
	s_waitcnt lgkmcnt(1)
	v_mfma_f32_16x16x32_bf16 v[174:177], v[100:103], v[162:165], 0
	v_mad_u32_u24 v103, v136, s0, v233
	v_mul_f32_e32 v109, 0x3fb8aa3b, v109
	v_add_u32_e32 v101, v107, v103
	v_mad_u32_u24 v102, v136, s0, v234
	v_exp_f32_e32 v241, v109
	ds_read2_b64 v[178:181], v101 offset1:4
	v_add_u32_e32 v101, v107, v102
	v_lshl_add_u32 v109, v108, 5, v105
	v_sub_f32_e32 v100, v197, v161
	ds_read2_b64 v[182:185], v101 offset1:4
	v_mad_u32_u24 v101, v136, s0, v109
	v_mul_f32_e32 v100, 0x3fb8aa3b, v100
	v_add_u32_e32 v101, 0xd800, v101
	v_exp_f32_e32 v100, v100
	v_cvt_pk_bf16_f32 v186, v167, v168
	v_cvt_pk_bf16_f32 v187, v199, v200
	v_cvt_pk_bf16_f32 v188, v201, v205
	v_cvt_pk_bf16_f32 v189, v206, v207
	ds_read2_b64 v[190:193], v101 offset1:4
	v_add_u32_e32 v101, 0xd800, v109
	v_add_u32_e32 v107, v101, v104
	ds_read2_b64 v[194:197], v107 offset1:4
	v_add_f32_e32 v107, v166, v240
	v_add_f32_e32 v107, v241, v107
	v_add_f32_e32 v167, v100, v107
	v_sub_f32_e32 v107, v198, v161
	v_mul_f32_e32 v107, 0x3fb8aa3b, v107
	v_exp_f32_e32 v168, v107
	v_add_u32_e32 v107, v101, v103
	s_waitcnt lgkmcnt(4)
; __device__ __forceinline__ unsigned cvt_pk_bf16(float lo, float hi) { unsigned r; asm volatile("v_cvt_pk_bf16_f32 %0, %1, %2" : "=v"(r) : "v"(lo), "v"(hi)); return r; }
; #define LAS __attribute__((address_space(3)))
; __device__ __forceinline__ void attn_item(const Params& p, LAS unsigned char* lds, const AttnItem& I, const AttnItem& N, u32x4 (&kr)[6], u32x4 (&vr)[6], u32x4 (&qr)[2][2],
;                                           const float (&gk)[8], const float (&gq)[2][8], int dry) {
;     ...
; #pragma unroll
;         for (int kp = 0; kp < 5; ++kp) {
;             u32x4 pk; pk.x = cvt_pk_bf16(s[2 * kp][0], s[2 * kp][1]); pk.y = cvt_pk_bf16(s[2 * kp][2], s[2 * kp][3]); pk.z = cvt_pk_bf16(s[2 * kp + 1][0], s[2 * kp + 1][1]); pk.w = cvt_pk_bf16(s[2 * kp + 1][2], s[2 * kp + 1][3]);
;             const bf16x8 pb = __builtin_bit_cast(bf16x8, pk);
; #pragma unroll
;             for (int mt = 0; mt < 4; ++mt) { const LAS bf16_t* vp = VT + (mt * 16 + fr) * VLD + blk * 128 + (ts + 2 * kp) * 16 + 4 * fq;
;                 const u32x2 lo = *(const LAS u32x2*)vp; const u32x2 hi = *(const LAS u32x2*)(vp + 16);
;                 u32x4 av; av.x = lo.x; av.y = lo.y; av.z = hi.x; av.w = hi.y;
;                 ao[mt] = __builtin_amdgcn_mfma_f32_16x16x32_bf16(__builtin_bit_cast(bf16x8, av), pb, ao[mt], 0, 0, 0); } }
;         const float inv = __builtin_amdgcn_rcpf(den);
; #pragma unroll
;         for (int mt = 0; mt < 4; ++mt) { u32x2 o; o.x = cvt_pk_bf16(ao[mt][0] * inv, ao[mt][1] * inv); o.y = cvt_pk_bf16(ao[mt][2] * inv, ao[mt][3] * inv);
;             if (!dry) *(u32x2*)(proj + tokq * PLD + qcol + mt * 16 + 4 * fq) = o; }
;         if (fq == 0 && !dry) lse[((size_t)gi * T + tokq) * 8 + h] = mx + __logf(den);
	v_mfma_f32_16x16x32_bf16 v[170:173], v[170:173], v[162:165], 0
	v_add_u32_e32 v101, v101, v102
	v_lshl_add_u32 v108, v158, 5, v105
	v_cmp_gt_i32_e64 s[6:7], 0, v143
	s_waitcnt lgkmcnt(3)
	v_mfma_f32_16x16x32_bf16 v[178:181], v[178:181], v[162:165], 0
	v_cmp_gt_i32_e64 s[4:5], 0, v150
	v_writelane_b32 v243, s17, 40
	v_cmp_eq_u32_e32 vcc, 0, v141
	s_waitcnt lgkmcnt(2)
	v_mfma_f32_16x16x32_bf16 v[162:165], v[182:185], v[162:165], 0
	ds_read2_b64 v[182:185], v107 offset1:4
	s_waitcnt lgkmcnt(2)
	v_mfma_f32_16x16x32_bf16 v[174:177], v[190:193], v[186:189], v[174:177]
	ds_read2_b64 v[190:193], v101 offset1:4
	v_mad_u32_u24 v101, v136, s0, v108
	v_add_u32_e32 v101, 0xd800, v101
	s_waitcnt lgkmcnt(2)
	v_mfma_f32_16x16x32_bf16 v[170:173], v[194:197], v[186:189], v[170:173]
	v_cvt_pk_bf16_f32 v194, v208, v209
	v_cvt_pk_bf16_f32 v195, v210, v211
	v_cvt_pk_bf16_f32 v196, v212, v213
	v_cvt_pk_bf16_f32 v197, v214, v215
	ds_read2_b64 v[198:201], v101 offset1:4
	v_add_u32_e32 v101, 0xd800, v108
	v_add_u32_e32 v107, v101, v104
	s_waitcnt lgkmcnt(2)
	v_mfma_f32_16x16x32_bf16 v[178:181], v[182:185], v[186:189], v[178:181]
	ds_read2_b64 v[182:185], v107 offset1:4
	v_sub_f32_e32 v107, v202, v161
	v_mul_f32_e32 v107, 0x3fb8aa3b, v107
	v_exp_f32_e32 v158, v107
	v_sub_f32_e32 v107, v203, v161
	v_mul_f32_e32 v107, 0x3fb8aa3b, v107
	v_exp_f32_e32 v202, v107
	v_add_u32_e32 v107, v101, v103
	s_waitcnt lgkmcnt(0)
	v_mfma_f32_16x16x32_bf16 v[170:173], v[182:185], v[194:197], v[170:173]
	ds_read2_b64 v[182:185], v107 offset1:4
	v_add_u32_e32 v101, v101, v102
	v_lshl_add_u32 v107, v159, 5, v105
	v_mfma_f32_16x16x32_bf16 v[162:165], v[190:193], v[186:189], v[162:165]
	ds_read2_b64 v[186:189], v101 offset1:4
	v_mad_u32_u24 v101, v136, s0, v107
	v_add_u32_e32 v101, 0xd800, v101
	v_mfma_f32_16x16x32_bf16 v[174:177], v[198:201], v[194:197], v[174:177]
	v_cvt_pk_bf16_f32 v190, v216, v217
	v_cvt_pk_bf16_f32 v191, v218, v219
	v_cvt_pk_bf16_f32 v192, v235, v236
	v_cvt_pk_bf16_f32 v193, v237, v238
	ds_read2_b64 v[198:201], v101 offset1:4
	v_add_u32_e32 v101, 0xd800, v107
	v_add_u32_e32 v159, v101, v104
	s_waitcnt lgkmcnt(2)
	v_mfma_f32_16x16x32_bf16 v[178:181], v[182:185], v[194:197], v[178:181]
	ds_read2_b64 v[182:185], v159 offset1:4
	v_add_f32_e32 v159, v168, v167
	v_sub_f32_e32 v167, v204, v161
	s_waitcnt lgkmcnt(0)
	v_mfma_f32_16x16x32_bf16 v[170:173], v[182:185], v[190:193], v[170:173]
	v_add_u32_e32 v182, v101, v103
	ds_read2_b64 v[182:185], v182 offset1:4
	v_add_u32_e32 v101, v101, v102
	v_mfma_f32_16x16x32_bf16 v[162:165], v[186:189], v[194:197], v[162:165]
	ds_read2_b64 v[186:189], v101 offset1:4
	v_mul_f32_e32 v167, 0x3fb8aa3b, v167
	v_lshl_add_u32 v105, v160, 5, v105
	v_exp_f32_e32 v167, v167
	v_cvt_pk_bf16_f32 v194, v239, v166
	v_cvt_pk_bf16_f32 v195, v241, v100
	v_mad_u32_u24 v100, v136, s0, v105
	v_add_u32_e32 v100, 0xd800, v100
	v_add_f32_e32 v159, v158, v159
	v_mfma_f32_16x16x32_bf16 v[174:177], v[198:201], v[190:193], v[174:177]
	v_cvt_pk_bf16_f32 v196, v168, v158
	v_cvt_pk_bf16_f32 v197, v202, v167
	ds_read2_b64 v[198:201], v100 offset1:4
	v_add_u32_e32 v100, 0xd800, v105
	v_add_f32_e32 v159, v202, v159
	v_add_u32_e32 v101, v100, v104
	s_waitcnt lgkmcnt(2)
	v_mfma_f32_16x16x32_bf16 v[178:181], v[182:185], v[190:193], v[178:181]
	ds_read2_b64 v[182:185], v101 offset1:4
	v_add_f32_e32 v101, v167, v159
	v_add_u32_e32 v158, v100, v103
	s_waitcnt lgkmcnt(2)
	v_mfma_f32_16x16x32_bf16 v[162:165], v[186:189], v[190:193], v[162:165]
	ds_read2_b64 v[186:189], v158 offset1:4
	ds_bpermute_b32 v158, v99, v101
	v_add_u32_e32 v100, v100, v102
	ds_read2_b64 v[190:193], v100 offset1:4
	s_waitcnt lgkmcnt(4)
	v_mfma_f32_16x16x32_bf16 v[174:177], v[198:201], v[194:197], v[174:177]
	s_waitcnt lgkmcnt(1)
	v_add_f32_e32 v158, v101, v158
	ds_bpermute_b32 v159, v106, v158
	v_mov_b64_e32 v[100:101], s[14:15]
	v_mad_i64_i32 v[100:101], s[0:1], v148, s17, v[100:101]
	v_mfma_f32_16x16x32_bf16 v[170:173], v[182:185], v[194:197], v[170:173]
	s_waitcnt lgkmcnt(0)
	v_add_f32_e32 v158, v158, v159
	v_rcp_f32_e32 v159, v158
	v_mad_u64_u32 v[166:167], s[0:1], v100, s33, v[96:97]
	v_mov_b32_e32 v160, v167
	v_mfma_f32_16x16x32_bf16 v[178:181], v[186:189], v[194:197], v[178:181]
	v_mad_u64_u32 v[182:183], s[0:1], v101, s33, v[160:161]
	v_mul_f32_e32 v160, v159, v174
	v_mul_f32_e32 v168, v159, v175
	v_cvt_pk_bf16_f32 v174, v160, v168
	v_mul_f32_e32 v160, v159, v176
	v_mfma_f32_16x16x32_bf16 v[162:165], v[190:193], v[194:197], v[162:165]
	v_mov_b32_e32 v167, v182
	v_mul_f32_e32 v168, v159, v177
	v_cvt_pk_bf16_f32 v175, v160, v168
	v_mul_f32_e32 v160, v159, v170
	global_store_dwordx2 v[166:167], v[174:175], off
	v_mul_f32_e32 v168, v159, v171
	v_cvt_pk_bf16_f32 v170, v160, v168
	v_mul_f32_e32 v160, v159, v172
	v_mul_f32_e32 v168, v159, v173
	v_cvt_pk_bf16_f32 v171, v160, v168
	v_mul_f32_e32 v160, v159, v178
	global_store_dwordx2 v[166:167], v[170:171], off offset:32
	v_mul_f32_e32 v168, v159, v179
	v_cvt_pk_bf16_f32 v170, v160, v168
	v_mul_f32_e32 v160, v159, v180
	s_movk_i32 s0, 0x80
	v_mul_f32_e32 v168, v159, v181
	v_cvt_pk_bf16_f32 v171, v160, v168
	v_mul_f32_e32 v160, v159, v162
	v_mul_f32_e32 v162, v159, v163
	v_cmp_gt_i32_e64 s[10:11], s0, v143
	v_cmp_gt_i32_e64 s[0:1], 0, v155
	global_store_dwordx2 v[166:167], v[170:171], off offset:64
	v_cvt_pk_bf16_f32 v162, v160, v162
	v_mul_f32_e32 v160, v159, v164
	v_mul_f32_e32 v159, v159, v165
	v_cvt_pk_bf16_f32 v163, v160, v159
	global_store_dwordx2 v[166:167], v[162:163], off offset:96
	s_mov_b64 s[16:17], exec
	v_writelane_b32 v242, vcc_lo, 4
	s_nop 1
	v_writelane_b32 v242, vcc_hi, 5
	s_and_b64 vcc, s[16:17], vcc
	s_mov_b64 exec, vcc
	s_cbranch_execz .LBB0_334
	s_mov_b32 s2, 0x800000
	v_cmp_gt_f32_e32 vcc, s2, v158
	s_mov_b32 s2, 0x3f317217
	s_nop 0
	v_cndmask_b32_e64 v141, 0, 32, vcc
	v_ldexp_f32 v141, v158, v141
	v_log_f32_e32 v141, v141
	v_cndmask_b32_e32 v143, 0, v227, vcc
	v_mul_f32_e32 v150, 0x3f317217, v141
	v_fma_f32 v150, v141, s2, -v150
	v_fmac_f32_e32 v150, 0x3377d1cf, v141
	s_mov_b32 s2, 0x7f800000
	v_fmac_f32_e32 v150, 0x3f317217, v141
	v_cmp_lt_f32_e64 vcc, |v141|, s2
	s_nop 1
	v_cndmask_b32_e32 v141, v141, v150, vcc
	v_readlane_b32 vcc_lo, v242, 2
	v_readlane_b32 vcc_hi, v242, 3
	v_sub_f32_e32 v141, v141, v143
	v_add_f32_e32 v141, v161, v141
	v_lshl_add_u64 v[100:101], v[100:101], 0, vcc
	v_readlane_b32 vcc_lo, v243, 38
	v_lshlrev_b64 v[100:101], 5, v[100:101]
	v_readlane_b32 vcc_hi, v243, 39
	s_nop 1
	v_lshl_add_u64 v[100:101], vcc, 0, v[100:101]
	global_store_dword v[100:101], v141, off
